# v21 + DMA issue sites: m0 write moved in front of the address add so the s_nop wait state is no longer needed (54 sites)
# baseline (speedup 1.0000x reference)
.LBB0_239:
	s_add_u32 s10, s12, 0xfff80080
	s_addc_u32 s11, s13, -1
	s_add_i32 s64, 0, 0x10000
	s_cmp_eq_u32 s70, 28
	s_cselect_b32 s39, s25, s11
	s_cselect_b32 s38, s43, s10
	s_cselect_b32 s15, s23, s69
	s_cselect_b32 s14, s67, s68
	s_add_i32 s65, 0, 0x14000
	v_add_u32_e32 v152, s64, v160
	v_add_u32_e32 v156, s65, v160
	ds_read_b128 v[140:143], v152
	ds_read_b128 v[144:147], v152 offset:1024
	ds_read_b128 v[148:151], v152 offset:2048
	ds_read_b128 v[152:155], v152 offset:3072
	ds_read_b128 v[162:165], v156
	ds_read_b128 v[166:169], v156 offset:1024
	ds_read_b128 v[170:173], v156 offset:2048
	ds_read_b128 v[180:183], v156 offset:3072
	v_lshl_add_u64 v[156:157], s[12:13], 0, v[138:139]
	s_add_i32 m0, s40, 0xc000
	ds_read_b128 v[184:187], v161
	ds_read_b128 v[188:191], v161 offset:1024
	ds_read_b128 v[192:195], v161 offset:2048
	ds_read_b128 v[196:199], v161 offset:3072
	ds_read_b128 v[200:203], v161 offset:4096
	ds_read_b128 v[204:207], v161 offset:5120
	ds_read_b128 v[208:211], v161 offset:6144
	ds_read_b128 v[212:215], v161 offset:7168
	global_load_lds_dwordx4 v[156:157], off
	s_add_i32 m0, s40, 0xe000
	v_lshl_add_u64 v[156:157], s[12:13], 0, v[136:137]
	global_load_lds_dwordx4 v[156:157], off
	s_waitcnt vmcnt(8)
	s_waitcnt lgkmcnt(0)
	s_barrier
	s_setprio 1
	s_waitcnt lgkmcnt(0)
	v_mfma_f32_16x16x32_bf16 v[126:129], v[140:143], v[184:187], v[126:129]
	v_mfma_f32_16x16x32_bf16 v[122:125], v[148:151], v[184:187], v[122:125]
	v_mfma_f32_16x16x32_bf16 v[110:113], v[140:143], v[192:195], v[110:113]
	v_mfma_f32_16x16x32_bf16 v[106:109], v[148:151], v[192:195], v[106:109]
	v_mfma_f32_16x16x32_bf16 v[94:97], v[140:143], v[200:203], v[94:97]
	v_mfma_f32_16x16x32_bf16 v[90:93], v[148:151], v[200:203], v[90:93]
	v_mfma_f32_16x16x32_bf16 v[78:81], v[140:143], v[208:211], v[78:81]
	v_mfma_f32_16x16x32_bf16 v[74:77], v[148:151], v[208:211], v[74:77]
	v_mfma_f32_16x16x32_bf16 v[126:129], v[144:147], v[188:191], v[126:129]
	v_mfma_f32_16x16x32_bf16 v[122:125], v[152:155], v[188:191], v[122:125]
	v_mfma_f32_16x16x32_bf16 v[110:113], v[144:147], v[196:199], v[110:113]
	v_mfma_f32_16x16x32_bf16 v[106:109], v[152:155], v[196:199], v[106:109]
	v_mfma_f32_16x16x32_bf16 v[94:97], v[144:147], v[204:207], v[94:97]
	v_mfma_f32_16x16x32_bf16 v[90:93], v[152:155], v[204:207], v[90:93]
	v_mfma_f32_16x16x32_bf16 v[78:81], v[144:147], v[212:215], v[78:81]
	v_mfma_f32_16x16x32_bf16 v[74:77], v[152:155], v[212:215], v[74:77]
	s_setprio 0
	s_setprio 1
	v_mfma_f32_16x16x32_bf16 v[118:121], v[162:165], v[184:187], v[118:121]
	v_mfma_f32_16x16x32_bf16 v[114:117], v[170:173], v[184:187], v[114:117]
	v_mfma_f32_16x16x32_bf16 v[102:105], v[162:165], v[192:195], v[102:105]
	v_mfma_f32_16x16x32_bf16 v[98:101], v[170:173], v[192:195], v[98:101]
	v_mfma_f32_16x16x32_bf16 v[86:89], v[162:165], v[200:203], v[86:89]
	v_mfma_f32_16x16x32_bf16 v[82:85], v[170:173], v[200:203], v[82:85]
	v_mfma_f32_16x16x32_bf16 v[70:73], v[162:165], v[208:211], v[70:73]
	v_mfma_f32_16x16x32_bf16 v[66:69], v[170:173], v[208:211], v[66:69]
	v_mfma_f32_16x16x32_bf16 v[118:121], v[166:169], v[188:191], v[118:121]
	v_mfma_f32_16x16x32_bf16 v[114:117], v[180:183], v[188:191], v[114:117]
	v_mfma_f32_16x16x32_bf16 v[102:105], v[166:169], v[196:199], v[102:105]
	v_mfma_f32_16x16x32_bf16 v[98:101], v[180:183], v[196:199], v[98:101]
	v_mfma_f32_16x16x32_bf16 v[86:89], v[166:169], v[204:207], v[86:89]
	v_mfma_f32_16x16x32_bf16 v[82:85], v[180:183], v[204:207], v[82:85]
	v_mfma_f32_16x16x32_bf16 v[70:73], v[166:169], v[212:215], v[70:73]
	v_mfma_f32_16x16x32_bf16 v[66:69], v[180:183], v[212:215], v[66:69]
	s_setprio 2
	s_barrier
	s_add_i32 s10, s64, s37
	v_lshl_add_u64 v[156:157], s[14:15], 0, v[0:1]
	s_mov_b32 m0, s10
	ds_read_b128 v[184:187], v161 offset:16384
	ds_read_b128 v[188:191], v161 offset:17408
	ds_read_b128 v[192:195], v161 offset:18432
	ds_read_b128 v[196:199], v161 offset:19456
	ds_read_b128 v[200:203], v161 offset:20480
	ds_read_b128 v[204:207], v161 offset:21504
	ds_read_b128 v[208:211], v161 offset:22528
	ds_read_b128 v[212:215], v161 offset:23552
	global_load_lds_dwordx4 v[156:157], off
	s_add_i32 m0, s10, 0x2000
	s_add_u32 s10, s14, 0x80000
	v_lshl_add_u64 v[174:175], s[14:15], 0, v[130:131]
	s_addc_u32 s11, s15, 0
	s_add_i32 s64, s65, s37
	global_load_lds_dwordx4 v[174:175], off
	v_lshl_add_u64 v[176:177], s[10:11], 0, v[0:1]
	s_mov_b32 m0, s64
	v_lshl_add_u64 v[178:179], s[38:39], 0, v[132:133]
	global_load_lds_dwordx4 v[176:177], off
	s_add_i32 m0, s64, 0x2000
	v_lshl_add_u64 v[176:177], s[10:11], 0, v[130:131]
	global_load_lds_dwordx4 v[176:177], off
	s_mov_b32 m0, s40
	v_lshl_add_u64 v[176:177], s[38:39], 0, v[134:135]
	global_load_lds_dwordx4 v[176:177], off
	s_mov_b32 m0, s41
	s_nop 0
	global_load_lds_dwordx4 v[178:179], off
	s_waitcnt vmcnt(8)
	s_waitcnt lgkmcnt(0)
	s_barrier
	s_setprio 1
	s_waitcnt lgkmcnt(0)
	v_mfma_f32_16x16x32_bf16 v[62:65], v[140:143], v[184:187], v[62:65]
	v_mfma_f32_16x16x32_bf16 v[58:61], v[148:151], v[184:187], v[58:61]
	v_mfma_f32_16x16x32_bf16 v[46:49], v[140:143], v[192:195], v[46:49]
	v_mfma_f32_16x16x32_bf16 v[42:45], v[148:151], v[192:195], v[42:45]
	v_mfma_f32_16x16x32_bf16 v[30:33], v[140:143], v[200:203], v[30:33]
	v_mfma_f32_16x16x32_bf16 v[26:29], v[148:151], v[200:203], v[26:29]
	v_mfma_f32_16x16x32_bf16 v[14:17], v[140:143], v[208:211], v[14:17]
	v_mfma_f32_16x16x32_bf16 v[10:13], v[148:151], v[208:211], v[10:13]
	v_mfma_f32_16x16x32_bf16 v[62:65], v[144:147], v[188:191], v[62:65]
	v_mfma_f32_16x16x32_bf16 v[58:61], v[152:155], v[188:191], v[58:61]
	v_mfma_f32_16x16x32_bf16 v[46:49], v[144:147], v[196:199], v[46:49]
	v_mfma_f32_16x16x32_bf16 v[42:45], v[152:155], v[196:199], v[42:45]
	v_mfma_f32_16x16x32_bf16 v[30:33], v[144:147], v[204:207], v[30:33]
	v_mfma_f32_16x16x32_bf16 v[26:29], v[152:155], v[204:207], v[26:29]
	v_mfma_f32_16x16x32_bf16 v[14:17], v[144:147], v[212:215], v[14:17]
	v_mfma_f32_16x16x32_bf16 v[10:13], v[152:155], v[212:215], v[10:13]
	s_setprio 0
	s_setprio 1
	v_mfma_f32_16x16x32_bf16 v[54:57], v[162:165], v[184:187], v[54:57]
	v_mfma_f32_16x16x32_bf16 v[50:53], v[170:173], v[184:187], v[50:53]
	v_mfma_f32_16x16x32_bf16 v[38:41], v[162:165], v[192:195], v[38:41]
	v_mfma_f32_16x16x32_bf16 v[34:37], v[170:173], v[192:195], v[34:37]
	v_mfma_f32_16x16x32_bf16 v[22:25], v[162:165], v[200:203], v[22:25]
	v_mfma_f32_16x16x32_bf16 v[18:21], v[170:173], v[200:203], v[18:21]
	v_mfma_f32_16x16x32_bf16 v[6:9], v[162:165], v[208:211], v[6:9]
	v_mfma_f32_16x16x32_bf16 v[2:5], v[170:173], v[208:211], v[2:5]
	v_mfma_f32_16x16x32_bf16 v[54:57], v[166:169], v[188:191], v[54:57]
	v_mfma_f32_16x16x32_bf16 v[50:53], v[180:183], v[188:191], v[50:53]
	v_mfma_f32_16x16x32_bf16 v[38:41], v[166:169], v[196:199], v[38:41]
	v_mfma_f32_16x16x32_bf16 v[34:37], v[180:183], v[196:199], v[34:37]
	v_mfma_f32_16x16x32_bf16 v[22:25], v[166:169], v[204:207], v[22:25]
	v_mfma_f32_16x16x32_bf16 v[18:21], v[180:183], v[204:207], v[18:21]
	v_mfma_f32_16x16x32_bf16 v[6:9], v[166:169], v[212:215], v[6:9]
	v_mfma_f32_16x16x32_bf16 v[2:5], v[180:183], v[212:215], v[2:5]
	s_setprio 2
	s_barrier
	s_add_i32 s64, 0, 0x18000
	s_add_i32 s65, 0, 0x1c000
	v_add_u32_e32 v152, s64, v160
	v_add_u32_e32 v180, s65, v160
	ds_read_b128 v[140:143], v152
	ds_read_b128 v[144:147], v152 offset:1024
	ds_read_b128 v[148:151], v152 offset:2048
	ds_read_b128 v[152:155], v152 offset:3072
	ds_read_b128 v[162:165], v180
	ds_read_b128 v[166:169], v180 offset:1024
	ds_read_b128 v[170:173], v180 offset:2048
	ds_read_b128 v[180:183], v180 offset:3072
	s_add_u32 s10, s38, 0x80000
	s_addc_u32 s11, s39, 0
	s_mov_b32 m0, s44
	v_lshl_add_u64 v[216:217], s[10:11], 0, v[134:135]
	ds_read_b128 v[184:187], v161 offset:32768
	ds_read_b128 v[188:191], v161 offset:33792
	ds_read_b128 v[192:195], v161 offset:34816
	ds_read_b128 v[196:199], v161 offset:35840
	ds_read_b128 v[200:203], v161 offset:36864
	ds_read_b128 v[204:207], v161 offset:37888
	ds_read_b128 v[208:211], v161 offset:38912
	ds_read_b128 v[212:215], v161 offset:39936
	global_load_lds_dwordx4 v[216:217], off
	s_mov_b32 m0, s45
	v_lshl_add_u64 v[216:217], s[10:11], 0, v[132:133]
	global_load_lds_dwordx4 v[216:217], off
	s_waitcnt vmcnt(8)
	s_waitcnt lgkmcnt(0)
	s_barrier
	s_setprio 1
	s_waitcnt lgkmcnt(0)
	v_mfma_f32_16x16x32_bf16 v[126:129], v[140:143], v[184:187], v[126:129]
	v_mfma_f32_16x16x32_bf16 v[122:125], v[148:151], v[184:187], v[122:125]
	v_mfma_f32_16x16x32_bf16 v[110:113], v[140:143], v[192:195], v[110:113]
	v_mfma_f32_16x16x32_bf16 v[106:109], v[148:151], v[192:195], v[106:109]
	v_mfma_f32_16x16x32_bf16 v[94:97], v[140:143], v[200:203], v[94:97]
	v_mfma_f32_16x16x32_bf16 v[90:93], v[148:151], v[200:203], v[90:93]
	v_mfma_f32_16x16x32_bf16 v[78:81], v[140:143], v[208:211], v[78:81]
	v_mfma_f32_16x16x32_bf16 v[74:77], v[148:151], v[208:211], v[74:77]
	v_mfma_f32_16x16x32_bf16 v[126:129], v[144:147], v[188:191], v[126:129]
	v_mfma_f32_16x16x32_bf16 v[122:125], v[152:155], v[188:191], v[122:125]
	v_mfma_f32_16x16x32_bf16 v[110:113], v[144:147], v[196:199], v[110:113]
	v_mfma_f32_16x16x32_bf16 v[106:109], v[152:155], v[196:199], v[106:109]
	v_mfma_f32_16x16x32_bf16 v[94:97], v[144:147], v[204:207], v[94:97]
	v_mfma_f32_16x16x32_bf16 v[90:93], v[152:155], v[204:207], v[90:93]
	v_mfma_f32_16x16x32_bf16 v[78:81], v[144:147], v[212:215], v[78:81]
	v_mfma_f32_16x16x32_bf16 v[74:77], v[152:155], v[212:215], v[74:77]
	s_setprio 0
	s_setprio 1
	v_mfma_f32_16x16x32_bf16 v[118:121], v[162:165], v[184:187], v[118:121]
	v_mfma_f32_16x16x32_bf16 v[114:117], v[170:173], v[184:187], v[114:117]
	v_mfma_f32_16x16x32_bf16 v[102:105], v[162:165], v[192:195], v[102:105]
	v_mfma_f32_16x16x32_bf16 v[98:101], v[170:173], v[192:195], v[98:101]
	v_mfma_f32_16x16x32_bf16 v[86:89], v[162:165], v[200:203], v[86:89]
	v_mfma_f32_16x16x32_bf16 v[82:85], v[170:173], v[200:203], v[82:85]
	v_mfma_f32_16x16x32_bf16 v[70:73], v[162:165], v[208:211], v[70:73]
	v_mfma_f32_16x16x32_bf16 v[66:69], v[170:173], v[208:211], v[66:69]
	v_mfma_f32_16x16x32_bf16 v[118:121], v[166:169], v[188:191], v[118:121]
	v_mfma_f32_16x16x32_bf16 v[114:117], v[180:183], v[188:191], v[114:117]
	v_mfma_f32_16x16x32_bf16 v[102:105], v[166:169], v[196:199], v[102:105]
	v_mfma_f32_16x16x32_bf16 v[98:101], v[180:183], v[196:199], v[98:101]
	v_mfma_f32_16x16x32_bf16 v[86:89], v[166:169], v[204:207], v[86:89]
	v_mfma_f32_16x16x32_bf16 v[82:85], v[180:183], v[204:207], v[82:85]
	v_mfma_f32_16x16x32_bf16 v[70:73], v[166:169], v[212:215], v[70:73]
	v_mfma_f32_16x16x32_bf16 v[66:69], v[180:183], v[212:215], v[66:69]
	s_setprio 2
	s_barrier
	s_add_i32 s10, s64, s37
	v_lshl_add_u64 v[156:157], v[156:157], 0, s[94:95]
	s_mov_b32 m0, s10
	ds_read_b128 v[184:187], v161 offset:49152
	ds_read_b128 v[188:191], v161 offset:50176
	ds_read_b128 v[192:195], v161 offset:51200
	ds_read_b128 v[196:199], v161 offset:52224
	ds_read_b128 v[200:203], v161 offset:53248
	ds_read_b128 v[204:207], v161 offset:54272
	ds_read_b128 v[208:211], v161 offset:55296
	ds_read_b128 v[212:215], v161 offset:56320
	global_load_lds_dwordx4 v[156:157], off
	s_add_i32 m0, s10, 0x2000
	s_add_u32 s10, s14, 0x80080
	v_lshl_add_u64 v[156:157], v[174:175], 0, s[94:95]
	s_addc_u32 s11, s15, 0
	s_add_i32 s14, s65, s37
	global_load_lds_dwordx4 v[156:157], off
	s_mov_b32 m0, s14
	v_lshl_add_u64 v[156:157], s[10:11], 0, v[0:1]
	global_load_lds_dwordx4 v[156:157], off
	s_add_i32 m0, s14, 0x2000
	v_lshl_add_u64 v[156:157], s[10:11], 0, v[130:131]
	global_load_lds_dwordx4 v[156:157], off
	s_mov_b32 m0, s60
	v_lshl_add_u64 v[156:157], v[176:177], 0, s[94:95]
	global_load_lds_dwordx4 v[156:157], off
	s_mov_b32 m0, s61
	v_lshl_add_u64 v[156:157], v[178:179], 0, s[94:95]
	global_load_lds_dwordx4 v[156:157], off
	s_waitcnt vmcnt(8)
	s_waitcnt lgkmcnt(0)
	s_barrier
	s_setprio 1
	s_waitcnt lgkmcnt(0)
	v_mfma_f32_16x16x32_bf16 v[62:65], v[140:143], v[184:187], v[62:65]
	v_mfma_f32_16x16x32_bf16 v[58:61], v[148:151], v[184:187], v[58:61]
	v_mfma_f32_16x16x32_bf16 v[46:49], v[140:143], v[192:195], v[46:49]
	v_mfma_f32_16x16x32_bf16 v[42:45], v[148:151], v[192:195], v[42:45]
	v_mfma_f32_16x16x32_bf16 v[30:33], v[140:143], v[200:203], v[30:33]
	v_mfma_f32_16x16x32_bf16 v[26:29], v[148:151], v[200:203], v[26:29]
	v_mfma_f32_16x16x32_bf16 v[14:17], v[140:143], v[208:211], v[14:17]
	v_mfma_f32_16x16x32_bf16 v[10:13], v[148:151], v[208:211], v[10:13]
	v_mfma_f32_16x16x32_bf16 v[62:65], v[144:147], v[188:191], v[62:65]
	v_mfma_f32_16x16x32_bf16 v[58:61], v[152:155], v[188:191], v[58:61]
	v_mfma_f32_16x16x32_bf16 v[46:49], v[144:147], v[196:199], v[46:49]
	v_mfma_f32_16x16x32_bf16 v[42:45], v[152:155], v[196:199], v[42:45]
	v_mfma_f32_16x16x32_bf16 v[30:33], v[144:147], v[204:207], v[30:33]
	v_mfma_f32_16x16x32_bf16 v[26:29], v[152:155], v[204:207], v[26:29]
	v_mfma_f32_16x16x32_bf16 v[14:17], v[144:147], v[212:215], v[14:17]
	v_mfma_f32_16x16x32_bf16 v[10:13], v[152:155], v[212:215], v[10:13]
	s_setprio 0
	s_setprio 1
	v_mfma_f32_16x16x32_bf16 v[54:57], v[162:165], v[184:187], v[54:57]
	v_mfma_f32_16x16x32_bf16 v[50:53], v[170:173], v[184:187], v[50:53]
	v_mfma_f32_16x16x32_bf16 v[38:41], v[162:165], v[192:195], v[38:41]
	v_mfma_f32_16x16x32_bf16 v[34:37], v[170:173], v[192:195], v[34:37]
	v_mfma_f32_16x16x32_bf16 v[22:25], v[162:165], v[200:203], v[22:25]
	v_mfma_f32_16x16x32_bf16 v[18:21], v[170:173], v[200:203], v[18:21]
	v_mfma_f32_16x16x32_bf16 v[6:9], v[162:165], v[208:211], v[6:9]
	v_mfma_f32_16x16x32_bf16 v[2:5], v[170:173], v[208:211], v[2:5]
	v_mfma_f32_16x16x32_bf16 v[54:57], v[166:169], v[188:191], v[54:57]
	v_mfma_f32_16x16x32_bf16 v[50:53], v[180:183], v[188:191], v[50:53]
	v_mfma_f32_16x16x32_bf16 v[38:41], v[166:169], v[196:199], v[38:41]
	v_mfma_f32_16x16x32_bf16 v[34:37], v[180:183], v[196:199], v[34:37]
	v_mfma_f32_16x16x32_bf16 v[22:25], v[166:169], v[204:207], v[22:25]
	v_mfma_f32_16x16x32_bf16 v[18:21], v[180:183], v[204:207], v[18:21]
	v_mfma_f32_16x16x32_bf16 v[6:9], v[166:169], v[212:215], v[6:9]
	v_mfma_f32_16x16x32_bf16 v[2:5], v[180:183], v[212:215], v[2:5]
	s_setprio 2
	s_barrier
	s_add_i32 s70, s70, 2
	s_add_u32 s68, s68, 0x100
	s_addc_u32 s69, s69, 0
	s_add_u32 s12, s12, 0x100
	s_addc_u32 s13, s13, 0
	s_cmp_gt_u32 s70, 29
	s_cbranch_scc0 .LBB0_239
	s_and_b64 vcc, exec, s[20:21]
	s_cbranch_vccz .LBB0_242
	s_barrier

.LBB0_341:
	s_add_u32 s10, s12, 0xfff00080
	s_addc_u32 s11, s13, -1
	s_add_i32 s64, 0, 0x10000
	s_cmp_eq_u32 s72, 4
	s_cselect_b32 s45, s25, s11
	s_cselect_b32 s44, s68, s10
	s_cselect_b32 s43, s23, s71
	s_cselect_b32 s42, s69, s70
	s_add_i32 s65, 0, 0x14000
	v_add_u32_e32 v152, s64, v162
	v_add_u32_e32 v172, s65, v162
	ds_read_b128 v[140:143], v152
	ds_read_b128 v[144:147], v152 offset:1024
	ds_read_b128 v[148:151], v152 offset:2048
	ds_read_b128 v[152:155], v152 offset:3072
	ds_read_b128 v[156:159], v172
	ds_read_b128 v[164:167], v172 offset:1024
	ds_read_b128 v[168:171], v172 offset:2048
	ds_read_b128 v[172:175], v172 offset:3072
	v_lshl_add_u64 v[176:177], s[12:13], 0, v[138:139]
	s_add_i32 m0, s33, 0xc000
	ds_read_b128 v[180:183], v163
	ds_read_b128 v[184:187], v163 offset:1024
	ds_read_b128 v[188:191], v163 offset:2048
	ds_read_b128 v[192:195], v163 offset:3072
	ds_read_b128 v[196:199], v163 offset:4096
	ds_read_b128 v[200:203], v163 offset:5120
	ds_read_b128 v[204:207], v163 offset:6144
	ds_read_b128 v[208:211], v163 offset:7168
	global_load_lds_dwordx4 v[176:177], off
	s_add_i32 m0, s33, 0xe000
	v_lshl_add_u64 v[176:177], s[12:13], 0, v[136:137]
	global_load_lds_dwordx4 v[176:177], off
	s_waitcnt vmcnt(8)
	s_waitcnt lgkmcnt(0)
	s_barrier
	s_setprio 1
	s_waitcnt lgkmcnt(0)
	v_mfma_f32_16x16x32_bf16 v[126:129], v[140:143], v[180:183], v[126:129]
	v_mfma_f32_16x16x32_bf16 v[122:125], v[148:151], v[180:183], v[122:125]
	v_mfma_f32_16x16x32_bf16 v[118:121], v[140:143], v[188:191], v[118:121]
	v_mfma_f32_16x16x32_bf16 v[114:117], v[148:151], v[188:191], v[114:117]
	v_mfma_f32_16x16x32_bf16 v[94:97], v[140:143], v[196:199], v[94:97]
	v_mfma_f32_16x16x32_bf16 v[90:93], v[148:151], v[196:199], v[90:93]
	v_mfma_f32_16x16x32_bf16 v[78:81], v[140:143], v[204:207], v[78:81]
	v_mfma_f32_16x16x32_bf16 v[74:77], v[148:151], v[204:207], v[74:77]
	v_mfma_f32_16x16x32_bf16 v[126:129], v[144:147], v[184:187], v[126:129]
	v_mfma_f32_16x16x32_bf16 v[122:125], v[152:155], v[184:187], v[122:125]
	v_mfma_f32_16x16x32_bf16 v[118:121], v[144:147], v[192:195], v[118:121]
	v_mfma_f32_16x16x32_bf16 v[114:117], v[152:155], v[192:195], v[114:117]
	v_mfma_f32_16x16x32_bf16 v[94:97], v[144:147], v[200:203], v[94:97]
	v_mfma_f32_16x16x32_bf16 v[90:93], v[152:155], v[200:203], v[90:93]
	v_mfma_f32_16x16x32_bf16 v[78:81], v[144:147], v[208:211], v[78:81]
	v_mfma_f32_16x16x32_bf16 v[74:77], v[152:155], v[208:211], v[74:77]
	s_setprio 0
	s_setprio 1
	v_mfma_f32_16x16x32_bf16 v[110:113], v[156:159], v[180:183], v[110:113]
	v_mfma_f32_16x16x32_bf16 v[106:109], v[168:171], v[180:183], v[106:109]
	v_mfma_f32_16x16x32_bf16 v[102:105], v[156:159], v[188:191], v[102:105]
	v_mfma_f32_16x16x32_bf16 v[98:101], v[168:171], v[188:191], v[98:101]
	v_mfma_f32_16x16x32_bf16 v[86:89], v[156:159], v[196:199], v[86:89]
	v_mfma_f32_16x16x32_bf16 v[82:85], v[168:171], v[196:199], v[82:85]
	v_mfma_f32_16x16x32_bf16 v[70:73], v[156:159], v[204:207], v[70:73]
	v_mfma_f32_16x16x32_bf16 v[66:69], v[168:171], v[204:207], v[66:69]
	v_mfma_f32_16x16x32_bf16 v[110:113], v[164:167], v[184:187], v[110:113]
	v_mfma_f32_16x16x32_bf16 v[106:109], v[172:175], v[184:187], v[106:109]
	v_mfma_f32_16x16x32_bf16 v[102:105], v[164:167], v[192:195], v[102:105]
	v_mfma_f32_16x16x32_bf16 v[98:101], v[172:175], v[192:195], v[98:101]
	v_mfma_f32_16x16x32_bf16 v[86:89], v[164:167], v[200:203], v[86:89]
	v_mfma_f32_16x16x32_bf16 v[82:85], v[172:175], v[200:203], v[82:85]
	v_mfma_f32_16x16x32_bf16 v[70:73], v[164:167], v[208:211], v[70:73]
	v_mfma_f32_16x16x32_bf16 v[66:69], v[172:175], v[208:211], v[66:69]
	s_setprio 2
	s_barrier
	s_add_i32 s10, s64, s28
	v_lshl_add_u64 v[176:177], s[42:43], 0, v[0:1]
	s_mov_b32 m0, s10
	ds_read_b128 v[180:183], v163 offset:16384
	ds_read_b128 v[184:187], v163 offset:17408
	ds_read_b128 v[188:191], v163 offset:18432
	ds_read_b128 v[192:195], v163 offset:19456
	ds_read_b128 v[196:199], v163 offset:20480
	ds_read_b128 v[200:203], v163 offset:21504
	ds_read_b128 v[204:207], v163 offset:22528
	ds_read_b128 v[208:211], v163 offset:23552
	global_load_lds_dwordx4 v[176:177], off
	s_add_i32 m0, s10, 0x2000
	s_add_u32 s10, s42, 0x20000
	v_lshl_add_u64 v[178:179], s[42:43], 0, v[130:131]
	s_addc_u32 s11, s43, 0
	s_add_i32 s64, s65, s28
	global_load_lds_dwordx4 v[178:179], off
	v_lshl_add_u64 v[212:213], s[10:11], 0, v[0:1]
	s_mov_b32 m0, s64
	v_lshl_add_u64 v[214:215], s[44:45], 0, v[132:133]
	global_load_lds_dwordx4 v[212:213], off
	s_add_i32 m0, s64, 0x2000
	v_lshl_add_u64 v[212:213], s[10:11], 0, v[130:131]
	global_load_lds_dwordx4 v[212:213], off
	s_mov_b32 m0, s33
	v_lshl_add_u64 v[212:213], s[44:45], 0, v[134:135]
	global_load_lds_dwordx4 v[212:213], off
	s_mov_b32 m0, s37
	s_nop 0
	global_load_lds_dwordx4 v[214:215], off
	s_waitcnt vmcnt(8)
	s_waitcnt lgkmcnt(0)
	s_barrier
	s_setprio 1
	s_waitcnt lgkmcnt(0)
	v_mfma_f32_16x16x32_bf16 v[62:65], v[140:143], v[180:183], v[62:65]
	v_mfma_f32_16x16x32_bf16 v[58:61], v[148:151], v[180:183], v[58:61]
	v_mfma_f32_16x16x32_bf16 v[46:49], v[140:143], v[188:191], v[46:49]
	v_mfma_f32_16x16x32_bf16 v[42:45], v[148:151], v[188:191], v[42:45]
	v_mfma_f32_16x16x32_bf16 v[30:33], v[140:143], v[196:199], v[30:33]
	v_mfma_f32_16x16x32_bf16 v[26:29], v[148:151], v[196:199], v[26:29]
	v_mfma_f32_16x16x32_bf16 v[14:17], v[140:143], v[204:207], v[14:17]
	v_mfma_f32_16x16x32_bf16 v[10:13], v[148:151], v[204:207], v[10:13]
	v_mfma_f32_16x16x32_bf16 v[62:65], v[144:147], v[184:187], v[62:65]
	v_mfma_f32_16x16x32_bf16 v[58:61], v[152:155], v[184:187], v[58:61]
	v_mfma_f32_16x16x32_bf16 v[46:49], v[144:147], v[192:195], v[46:49]
	v_mfma_f32_16x16x32_bf16 v[42:45], v[152:155], v[192:195], v[42:45]
	v_mfma_f32_16x16x32_bf16 v[30:33], v[144:147], v[200:203], v[30:33]
	v_mfma_f32_16x16x32_bf16 v[26:29], v[152:155], v[200:203], v[26:29]
	v_mfma_f32_16x16x32_bf16 v[14:17], v[144:147], v[208:211], v[14:17]
	v_mfma_f32_16x16x32_bf16 v[10:13], v[152:155], v[208:211], v[10:13]
	s_setprio 0
	s_setprio 1
	v_mfma_f32_16x16x32_bf16 v[54:57], v[156:159], v[180:183], v[54:57]
	v_mfma_f32_16x16x32_bf16 v[50:53], v[168:171], v[180:183], v[50:53]
	v_mfma_f32_16x16x32_bf16 v[38:41], v[156:159], v[188:191], v[38:41]
	v_mfma_f32_16x16x32_bf16 v[34:37], v[168:171], v[188:191], v[34:37]
	v_mfma_f32_16x16x32_bf16 v[22:25], v[156:159], v[196:199], v[22:25]
	v_mfma_f32_16x16x32_bf16 v[18:21], v[168:171], v[196:199], v[18:21]
	v_mfma_f32_16x16x32_bf16 v[6:9], v[156:159], v[204:207], v[6:9]
	v_mfma_f32_16x16x32_bf16 v[2:5], v[168:171], v[204:207], v[2:5]
	v_mfma_f32_16x16x32_bf16 v[54:57], v[164:167], v[184:187], v[54:57]
	v_mfma_f32_16x16x32_bf16 v[50:53], v[172:175], v[184:187], v[50:53]
	v_mfma_f32_16x16x32_bf16 v[38:41], v[164:167], v[192:195], v[38:41]
	v_mfma_f32_16x16x32_bf16 v[34:37], v[172:175], v[192:195], v[34:37]
	v_mfma_f32_16x16x32_bf16 v[22:25], v[164:167], v[200:203], v[22:25]
	v_mfma_f32_16x16x32_bf16 v[18:21], v[172:175], v[200:203], v[18:21]
	v_mfma_f32_16x16x32_bf16 v[6:9], v[164:167], v[208:211], v[6:9]
	v_mfma_f32_16x16x32_bf16 v[2:5], v[172:175], v[208:211], v[2:5]
	s_setprio 2
	s_barrier
	s_add_i32 s64, 0, 0x18000
	s_add_i32 s65, 0, 0x1c000
	v_add_u32_e32 v152, s64, v162
	v_add_u32_e32 v172, s65, v162
	ds_read_b128 v[140:143], v152
	ds_read_b128 v[144:147], v152 offset:1024
	ds_read_b128 v[148:151], v152 offset:2048
	ds_read_b128 v[152:155], v152 offset:3072
	ds_read_b128 v[156:159], v172
	ds_read_b128 v[164:167], v172 offset:1024
	ds_read_b128 v[168:171], v172 offset:2048
	ds_read_b128 v[172:175], v172 offset:3072
	s_add_u32 s10, s44, 0x100000
	s_addc_u32 s11, s45, 0
	s_mov_b32 m0, s40
	v_lshl_add_u64 v[216:217], s[10:11], 0, v[134:135]
	ds_read_b128 v[180:183], v163 offset:32768
	ds_read_b128 v[184:187], v163 offset:33792
	ds_read_b128 v[188:191], v163 offset:34816
	ds_read_b128 v[192:195], v163 offset:35840
	ds_read_b128 v[196:199], v163 offset:36864
	ds_read_b128 v[200:203], v163 offset:37888
	ds_read_b128 v[204:207], v163 offset:38912
	ds_read_b128 v[208:211], v163 offset:39936
	global_load_lds_dwordx4 v[216:217], off
	s_mov_b32 m0, s41
	v_lshl_add_u64 v[216:217], s[10:11], 0, v[132:133]
	global_load_lds_dwordx4 v[216:217], off
	s_waitcnt vmcnt(8)
	s_waitcnt lgkmcnt(0)
	s_barrier
	s_setprio 1
	s_waitcnt lgkmcnt(0)
	v_mfma_f32_16x16x32_bf16 v[126:129], v[140:143], v[180:183], v[126:129]
	v_mfma_f32_16x16x32_bf16 v[122:125], v[148:151], v[180:183], v[122:125]
	v_mfma_f32_16x16x32_bf16 v[118:121], v[140:143], v[188:191], v[118:121]
	v_mfma_f32_16x16x32_bf16 v[114:117], v[148:151], v[188:191], v[114:117]
	v_mfma_f32_16x16x32_bf16 v[94:97], v[140:143], v[196:199], v[94:97]
	v_mfma_f32_16x16x32_bf16 v[90:93], v[148:151], v[196:199], v[90:93]
	v_mfma_f32_16x16x32_bf16 v[78:81], v[140:143], v[204:207], v[78:81]
	v_mfma_f32_16x16x32_bf16 v[74:77], v[148:151], v[204:207], v[74:77]
	v_mfma_f32_16x16x32_bf16 v[126:129], v[144:147], v[184:187], v[126:129]
	v_mfma_f32_16x16x32_bf16 v[122:125], v[152:155], v[184:187], v[122:125]
	v_mfma_f32_16x16x32_bf16 v[118:121], v[144:147], v[192:195], v[118:121]
	v_mfma_f32_16x16x32_bf16 v[114:117], v[152:155], v[192:195], v[114:117]
	v_mfma_f32_16x16x32_bf16 v[94:97], v[144:147], v[200:203], v[94:97]
	v_mfma_f32_16x16x32_bf16 v[90:93], v[152:155], v[200:203], v[90:93]
	v_mfma_f32_16x16x32_bf16 v[78:81], v[144:147], v[208:211], v[78:81]
	v_mfma_f32_16x16x32_bf16 v[74:77], v[152:155], v[208:211], v[74:77]
	s_setprio 0
	s_setprio 1
	v_mfma_f32_16x16x32_bf16 v[110:113], v[156:159], v[180:183], v[110:113]
	v_mfma_f32_16x16x32_bf16 v[106:109], v[168:171], v[180:183], v[106:109]
	v_mfma_f32_16x16x32_bf16 v[102:105], v[156:159], v[188:191], v[102:105]
	v_mfma_f32_16x16x32_bf16 v[98:101], v[168:171], v[188:191], v[98:101]
	v_mfma_f32_16x16x32_bf16 v[86:89], v[156:159], v[196:199], v[86:89]
	v_mfma_f32_16x16x32_bf16 v[82:85], v[168:171], v[196:199], v[82:85]
	v_mfma_f32_16x16x32_bf16 v[70:73], v[156:159], v[204:207], v[70:73]
	v_mfma_f32_16x16x32_bf16 v[66:69], v[168:171], v[204:207], v[66:69]
	v_mfma_f32_16x16x32_bf16 v[110:113], v[164:167], v[184:187], v[110:113]
	v_mfma_f32_16x16x32_bf16 v[106:109], v[172:175], v[184:187], v[106:109]
	v_mfma_f32_16x16x32_bf16 v[102:105], v[164:167], v[192:195], v[102:105]
	v_mfma_f32_16x16x32_bf16 v[98:101], v[172:175], v[192:195], v[98:101]
	v_mfma_f32_16x16x32_bf16 v[86:89], v[164:167], v[200:203], v[86:89]
	v_mfma_f32_16x16x32_bf16 v[82:85], v[172:175], v[200:203], v[82:85]
	v_mfma_f32_16x16x32_bf16 v[70:73], v[164:167], v[208:211], v[70:73]
	v_mfma_f32_16x16x32_bf16 v[66:69], v[172:175], v[208:211], v[66:69]
	s_setprio 2
	s_barrier
	s_add_i32 s10, s64, s28
	v_lshl_add_u64 v[176:177], v[176:177], 0, s[94:95]
	s_mov_b32 m0, s10
	ds_read_b128 v[180:183], v163 offset:49152
	ds_read_b128 v[184:187], v163 offset:50176
	ds_read_b128 v[188:191], v163 offset:51200
	ds_read_b128 v[192:195], v163 offset:52224
	ds_read_b128 v[196:199], v163 offset:53248
	ds_read_b128 v[200:203], v163 offset:54272
	ds_read_b128 v[204:207], v163 offset:55296
	ds_read_b128 v[208:211], v163 offset:56320
	global_load_lds_dwordx4 v[176:177], off
	s_add_i32 m0, s10, 0x2000
	s_add_u32 s10, s42, 0x20080
	v_lshl_add_u64 v[176:177], v[178:179], 0, s[94:95]
	s_addc_u32 s11, s43, 0
	s_add_i32 s42, s65, s28
	global_load_lds_dwordx4 v[176:177], off
	s_mov_b32 m0, s42
	v_lshl_add_u64 v[176:177], s[10:11], 0, v[0:1]
	global_load_lds_dwordx4 v[176:177], off
	s_add_i32 m0, s42, 0x2000
	v_lshl_add_u64 v[176:177], s[10:11], 0, v[130:131]
	global_load_lds_dwordx4 v[176:177], off
	s_mov_b32 m0, s58
	v_lshl_add_u64 v[176:177], v[212:213], 0, s[94:95]
	global_load_lds_dwordx4 v[176:177], off
	s_mov_b32 m0, s59
	v_lshl_add_u64 v[176:177], v[214:215], 0, s[94:95]
	global_load_lds_dwordx4 v[176:177], off
	s_waitcnt vmcnt(8)
	s_waitcnt lgkmcnt(0)
	s_barrier
	s_setprio 1
	s_waitcnt lgkmcnt(0)
	v_mfma_f32_16x16x32_bf16 v[62:65], v[140:143], v[180:183], v[62:65]
	v_mfma_f32_16x16x32_bf16 v[58:61], v[148:151], v[180:183], v[58:61]
	v_mfma_f32_16x16x32_bf16 v[46:49], v[140:143], v[188:191], v[46:49]
	v_mfma_f32_16x16x32_bf16 v[42:45], v[148:151], v[188:191], v[42:45]
	v_mfma_f32_16x16x32_bf16 v[30:33], v[140:143], v[196:199], v[30:33]
	v_mfma_f32_16x16x32_bf16 v[26:29], v[148:151], v[196:199], v[26:29]
	v_mfma_f32_16x16x32_bf16 v[14:17], v[140:143], v[204:207], v[14:17]
	v_mfma_f32_16x16x32_bf16 v[10:13], v[148:151], v[204:207], v[10:13]
	v_mfma_f32_16x16x32_bf16 v[62:65], v[144:147], v[184:187], v[62:65]
	v_mfma_f32_16x16x32_bf16 v[58:61], v[152:155], v[184:187], v[58:61]
	v_mfma_f32_16x16x32_bf16 v[46:49], v[144:147], v[192:195], v[46:49]
	v_mfma_f32_16x16x32_bf16 v[42:45], v[152:155], v[192:195], v[42:45]
	v_mfma_f32_16x16x32_bf16 v[30:33], v[144:147], v[200:203], v[30:33]
	v_mfma_f32_16x16x32_bf16 v[26:29], v[152:155], v[200:203], v[26:29]
	v_mfma_f32_16x16x32_bf16 v[14:17], v[144:147], v[208:211], v[14:17]
	v_mfma_f32_16x16x32_bf16 v[10:13], v[152:155], v[208:211], v[10:13]
	s_setprio 0
	s_setprio 1
	v_mfma_f32_16x16x32_bf16 v[54:57], v[156:159], v[180:183], v[54:57]
	v_mfma_f32_16x16x32_bf16 v[50:53], v[168:171], v[180:183], v[50:53]
	v_mfma_f32_16x16x32_bf16 v[38:41], v[156:159], v[188:191], v[38:41]
	v_mfma_f32_16x16x32_bf16 v[34:37], v[168:171], v[188:191], v[34:37]
	v_mfma_f32_16x16x32_bf16 v[22:25], v[156:159], v[196:199], v[22:25]
	v_mfma_f32_16x16x32_bf16 v[18:21], v[168:171], v[196:199], v[18:21]
	v_mfma_f32_16x16x32_bf16 v[6:9], v[156:159], v[204:207], v[6:9]
	v_mfma_f32_16x16x32_bf16 v[2:5], v[168:171], v[204:207], v[2:5]
	v_mfma_f32_16x16x32_bf16 v[54:57], v[164:167], v[184:187], v[54:57]
	v_mfma_f32_16x16x32_bf16 v[50:53], v[172:175], v[184:187], v[50:53]
	v_mfma_f32_16x16x32_bf16 v[38:41], v[164:167], v[192:195], v[38:41]
	v_mfma_f32_16x16x32_bf16 v[34:37], v[172:175], v[192:195], v[34:37]
	v_mfma_f32_16x16x32_bf16 v[22:25], v[164:167], v[200:203], v[22:25]
	v_mfma_f32_16x16x32_bf16 v[18:21], v[172:175], v[200:203], v[18:21]
	v_mfma_f32_16x16x32_bf16 v[6:9], v[164:167], v[208:211], v[6:9]
	v_mfma_f32_16x16x32_bf16 v[2:5], v[172:175], v[208:211], v[2:5]
	s_setprio 2
	s_barrier
	s_add_i32 s72, s72, 2
	s_add_u32 s70, s70, 0x100
	s_addc_u32 s71, s71, 0
	s_add_u32 s12, s12, 0x100
	s_addc_u32 s13, s13, 0
	s_cmp_gt_u32 s72, 5
	s_cbranch_scc0 .LBB0_341
	s_and_b64 vcc, exec, s[20:21]
	s_cbranch_vccz .LBB0_344
	s_barrier

.LBB0_360:
	s_ashr_i32 s57, s56, 31
	s_lshl_b64 s[10:11], s[56:57], 21
	s_add_u32 s60, s0, s10
	s_addc_u32 s61, s1, s11
	s_and_b64 s[10:11], s[12:13], exec
	s_cselect_b32 s73, s61, s15
	s_cselect_b32 s72, s60, s14
	s_ashr_i32 s45, s44, 31
	s_lshl_b64 s[10:11], s[44:45], 17
	s_add_u32 s62, s33, s10
	s_addc_u32 s63, s37, s11
	s_and_b64 s[10:11], s[12:13], exec
	s_cselect_b32 s71, s63, s69
	s_cselect_b32 s70, s62, s68
	s_add_i32 vcc_hi, 0, 0x10000
	s_add_i32 s91, 0, 0x14000
	v_add_u32_e32 v0, vcc_hi, v208
	v_add_u32_e32 v216, s91, v208
	ds_read_b128 v[2:5], v0
	ds_read_b128 v[6:9], v0 offset:1024
	ds_read_b128 v[10:13], v0 offset:2048
	ds_read_b128 v[14:17], v0 offset:3072
	ds_read_b128 v[18:21], v216
	ds_read_b128 v[22:25], v216 offset:1024
	ds_read_b128 v[26:29], v216 offset:2048
	ds_read_b128 v[30:33], v216 offset:3072
	v_mov_b32_e32 v237, 0xc00
	s_mov_b32 s80, s54
	s_add_u32 s64, s14, 0x100080
	s_addc_u32 s65, s15, 0
	s_add_i32 s11, s40, 0xc000
	v_lshl_add_u64 v[66:67], s[64:65], 0, v[136:137]
	s_mov_b32 m0, s11
	s_add_i32 s45, s40, 0xe000
	ds_read_b128 v[34:37], v209
	ds_read_b128 v[38:41], v209 offset:1024
	ds_read_b128 v[42:45], v209 offset:2048
	ds_read_b128 v[46:49], v209 offset:3072
	ds_read_b128 v[50:53], v209 offset:4096
	ds_read_b128 v[54:57], v209 offset:5120
	ds_read_b128 v[58:61], v209 offset:6144
	ds_read_b128 v[62:65], v209 offset:7168
	global_load_lds_dwordx4 v[66:67], off
	s_mov_b32 m0, s45
	v_lshl_add_u64 v[66:67], s[64:65], 0, v[132:133]
	global_load_lds_dwordx4 v[66:67], off
	s_waitcnt vmcnt(8)
	s_waitcnt lgkmcnt(0)
	s_barrier
	s_setprio 1
	s_waitcnt lgkmcnt(0)
	v_mfma_f32_16x16x32_bf16 v[66:69], v[2:5], v[34:37], 0
	v_mfma_f32_16x16x32_bf16 v[70:73], v[10:13], v[34:37], 0
	v_mfma_f32_16x16x32_bf16 v[74:77], v[2:5], v[42:45], 0
	v_mfma_f32_16x16x32_bf16 v[78:81], v[10:13], v[42:45], 0
	v_mfma_f32_16x16x32_bf16 v[82:85], v[2:5], v[50:53], 0
	v_mfma_f32_16x16x32_bf16 v[86:89], v[10:13], v[50:53], 0
	v_mfma_f32_16x16x32_bf16 v[90:93], v[2:5], v[58:61], 0
	v_mfma_f32_16x16x32_bf16 v[94:97], v[10:13], v[58:61], 0
	v_mfma_f32_16x16x32_bf16 v[66:69], v[6:9], v[38:41], v[66:69]
	v_mfma_f32_16x16x32_bf16 v[70:73], v[14:17], v[38:41], v[70:73]
	v_mfma_f32_16x16x32_bf16 v[74:77], v[6:9], v[46:49], v[74:77]
	v_mfma_f32_16x16x32_bf16 v[78:81], v[14:17], v[46:49], v[78:81]
	v_mfma_f32_16x16x32_bf16 v[82:85], v[6:9], v[54:57], v[82:85]
	v_mfma_f32_16x16x32_bf16 v[86:89], v[14:17], v[54:57], v[86:89]
	v_mfma_f32_16x16x32_bf16 v[90:93], v[6:9], v[62:65], v[90:93]
	v_mfma_f32_16x16x32_bf16 v[94:97], v[14:17], v[62:65], v[94:97]
	s_setprio 0
	s_setprio 1
	v_mfma_f32_16x16x32_bf16 v[98:101], v[18:21], v[34:37], 0
	v_mfma_f32_16x16x32_bf16 v[34:37], v[26:29], v[34:37], 0
	v_mfma_f32_16x16x32_bf16 v[98:101], v[22:25], v[38:41], v[98:101]
	v_mfma_f32_16x16x32_bf16 v[34:37], v[30:33], v[38:41], v[34:37]
	v_mfma_f32_16x16x32_bf16 v[38:41], v[18:21], v[42:45], 0
	v_mfma_f32_16x16x32_bf16 v[42:45], v[26:29], v[42:45], 0
	v_mfma_f32_16x16x32_bf16 v[38:41], v[22:25], v[46:49], v[38:41]
	v_mfma_f32_16x16x32_bf16 v[42:45], v[30:33], v[46:49], v[42:45]
	v_mfma_f32_16x16x32_bf16 v[46:49], v[18:21], v[50:53], 0
	v_mfma_f32_16x16x32_bf16 v[50:53], v[26:29], v[50:53], 0
	v_mfma_f32_16x16x32_bf16 v[46:49], v[22:25], v[54:57], v[46:49]
	v_mfma_f32_16x16x32_bf16 v[50:53], v[30:33], v[54:57], v[50:53]
	v_mfma_f32_16x16x32_bf16 v[54:57], v[18:21], v[58:61], 0
	v_mfma_f32_16x16x32_bf16 v[58:61], v[26:29], v[58:61], 0
	v_mfma_f32_16x16x32_bf16 v[54:57], v[22:25], v[62:65], v[54:57]
	v_mfma_f32_16x16x32_bf16 v[58:61], v[30:33], v[62:65], v[58:61]
	s_setprio 2
	s_barrier
	s_add_i32 vcc_hi, vcc_hi, s28
	v_lshl_add_u64 v[174:175], s[68:69], 0, v[134:135]
	s_add_i32 s57, vcc_hi, 0x2000
	v_lshl_add_u64 v[138:139], v[174:175], 0, s[96:97]
	s_mov_b32 m0, vcc_hi
	v_lshl_add_u64 v[176:177], s[68:69], 0, v[130:131]
	s_add_u32 s64, s68, 0x10100
	ds_read_b128 v[62:65], v209 offset:16384
	ds_read_b128 v[102:105], v209 offset:17408
	ds_read_b128 v[106:109], v209 offset:18432
	ds_read_b128 v[110:113], v209 offset:19456
	ds_read_b128 v[114:117], v209 offset:20480
	ds_read_b128 v[118:121], v209 offset:21504
	ds_read_b128 v[122:125], v209 offset:22528
	ds_read_b128 v[126:129], v209 offset:23552
	global_load_lds_dwordx4 v[138:139], off
	v_lshl_add_u64 v[138:139], v[176:177], 0, s[96:97]
	s_mov_b32 m0, s57
	s_addc_u32 s65, s69, 0
	s_add_i32 s91, s91, s28
	global_load_lds_dwordx4 v[138:139], off
	v_lshl_add_u64 v[138:139], s[64:65], 0, v[134:135]
	s_mov_b32 m0, s91
	s_add_i32 vcc_lo, s91, 0x2000
	global_load_lds_dwordx4 v[138:139], off
	v_lshl_add_u64 v[138:139], s[64:65], 0, v[130:131]
	s_mov_b32 m0, vcc_lo
	v_lshl_add_u64 v[178:179], s[14:15], 0, v[136:137]
	global_load_lds_dwordx4 v[138:139], off
	v_lshl_add_u64 v[138:139], v[178:179], 0, s[96:97]
	s_mov_b32 m0, s40
	v_lshl_add_u64 v[204:205], s[14:15], 0, v[132:133]
	global_load_lds_dwordx4 v[138:139], off
	s_mov_b32 m0, s41
	v_lshl_add_u64 v[138:139], v[204:205], 0, s[96:97]
	global_load_lds_dwordx4 v[138:139], off
	s_waitcnt vmcnt(8)
	s_waitcnt lgkmcnt(0)
	s_barrier
	s_setprio 1
	s_waitcnt lgkmcnt(0)
	v_mfma_f32_16x16x32_bf16 v[138:141], v[2:5], v[62:65], 0
	v_mfma_f32_16x16x32_bf16 v[146:149], v[2:5], v[106:109], 0
	v_mfma_f32_16x16x32_bf16 v[154:157], v[2:5], v[114:117], 0
	v_mfma_f32_16x16x32_bf16 v[2:5], v[2:5], v[122:125], 0
	v_mfma_f32_16x16x32_bf16 v[138:141], v[6:9], v[102:105], v[138:141]
	v_mfma_f32_16x16x32_bf16 v[146:149], v[6:9], v[110:113], v[146:149]
	v_mfma_f32_16x16x32_bf16 v[154:157], v[6:9], v[118:121], v[154:157]
	v_mfma_f32_16x16x32_bf16 v[2:5], v[6:9], v[126:129], v[2:5]
	v_mfma_f32_16x16x32_bf16 v[6:9], v[10:13], v[122:125], 0
	v_mfma_f32_16x16x32_bf16 v[142:145], v[10:13], v[62:65], 0
	v_mfma_f32_16x16x32_bf16 v[150:153], v[10:13], v[106:109], 0
	v_mfma_f32_16x16x32_bf16 v[158:161], v[10:13], v[114:117], 0
	v_mfma_f32_16x16x32_bf16 v[6:9], v[14:17], v[126:129], v[6:9]
	v_mfma_f32_16x16x32_bf16 v[142:145], v[14:17], v[102:105], v[142:145]
	v_mfma_f32_16x16x32_bf16 v[150:153], v[14:17], v[110:113], v[150:153]
	v_mfma_f32_16x16x32_bf16 v[158:161], v[14:17], v[118:121], v[158:161]
	s_setprio 0
	s_setprio 1
	v_mfma_f32_16x16x32_bf16 v[10:13], v[18:21], v[62:65], 0
	v_mfma_f32_16x16x32_bf16 v[14:17], v[26:29], v[62:65], 0
	v_mfma_f32_16x16x32_bf16 v[10:13], v[22:25], v[102:105], v[10:13]
	v_mfma_f32_16x16x32_bf16 v[14:17], v[30:33], v[102:105], v[14:17]
	v_mfma_f32_16x16x32_bf16 v[62:65], v[18:21], v[106:109], 0
	v_mfma_f32_16x16x32_bf16 v[102:105], v[26:29], v[106:109], 0
	v_mfma_f32_16x16x32_bf16 v[106:109], v[18:21], v[114:117], 0
	v_mfma_f32_16x16x32_bf16 v[18:21], v[18:21], v[122:125], 0
	v_mfma_f32_16x16x32_bf16 v[62:65], v[22:25], v[110:113], v[62:65]
	v_mfma_f32_16x16x32_bf16 v[102:105], v[30:33], v[110:113], v[102:105]
	v_mfma_f32_16x16x32_bf16 v[106:109], v[22:25], v[118:121], v[106:109]
	v_mfma_f32_16x16x32_bf16 v[110:113], v[26:29], v[114:117], 0
	v_mfma_f32_16x16x32_bf16 v[18:21], v[22:25], v[126:129], v[18:21]
	v_mfma_f32_16x16x32_bf16 v[22:25], v[26:29], v[122:125], 0
	v_mfma_f32_16x16x32_bf16 v[110:113], v[30:33], v[118:121], v[110:113]
	v_mfma_f32_16x16x32_bf16 v[22:25], v[30:33], v[126:129], v[22:25]
	s_setprio 2
	s_barrier
	s_add_i32 s10, 0, 0x18000
	s_add_i32 s16, 0, 0x1c000
	v_add_u32_e32 v226, s10, v208
	v_add_u32_e32 v227, s16, v208
	ds_read_b128 v[26:29], v226
	ds_read_b128 v[30:33], v226 offset:1024
	ds_read_b128 v[114:117], v226 offset:2048
	ds_read_b128 v[118:121], v226 offset:3072
	ds_read_b128 v[122:125], v227
	ds_read_b128 v[126:129], v227 offset:1024
	ds_read_b128 v[162:165], v227 offset:2048
	ds_read_b128 v[166:169], v227 offset:3072
	s_add_u32 s64, s14, 0x100100
	s_addc_u32 s65, s15, 0
	s_mov_b32 m0, s48
	v_lshl_add_u64 v[214:215], s[64:65], 0, v[136:137]
	ds_read_b128 v[170:173], v209 offset:32768
	ds_read_b128 v[180:183], v209 offset:33792
	ds_read_b128 v[184:187], v209 offset:34816
	ds_read_b128 v[188:191], v209 offset:35840
	ds_read_b128 v[192:195], v209 offset:36864
	ds_read_b128 v[196:199], v209 offset:37888
	ds_read_b128 v[200:203], v209 offset:38912
	ds_read_b128 v[210:213], v209 offset:39936
	global_load_lds_dwordx4 v[214:215], off
	s_mov_b32 m0, s52
	v_lshl_add_u64 v[214:215], s[64:65], 0, v[132:133]
	global_load_lds_dwordx4 v[214:215], off
	s_waitcnt vmcnt(8)
	s_waitcnt lgkmcnt(0)
	s_barrier
	s_setprio 1
	s_waitcnt lgkmcnt(0)
	v_mfma_f32_16x16x32_bf16 v[66:69], v[26:29], v[170:173], v[66:69]
	v_mfma_f32_16x16x32_bf16 v[70:73], v[114:117], v[170:173], v[70:73]
	v_mfma_f32_16x16x32_bf16 v[74:77], v[26:29], v[184:187], v[74:77]
	v_mfma_f32_16x16x32_bf16 v[78:81], v[114:117], v[184:187], v[78:81]
	v_mfma_f32_16x16x32_bf16 v[82:85], v[26:29], v[192:195], v[82:85]
	v_mfma_f32_16x16x32_bf16 v[86:89], v[114:117], v[192:195], v[86:89]
	v_mfma_f32_16x16x32_bf16 v[90:93], v[26:29], v[200:203], v[90:93]
	v_mfma_f32_16x16x32_bf16 v[94:97], v[114:117], v[200:203], v[94:97]
	v_mfma_f32_16x16x32_bf16 v[66:69], v[30:33], v[180:183], v[66:69]
	v_mfma_f32_16x16x32_bf16 v[70:73], v[118:121], v[180:183], v[70:73]
	v_mfma_f32_16x16x32_bf16 v[74:77], v[30:33], v[188:191], v[74:77]
	v_mfma_f32_16x16x32_bf16 v[78:81], v[118:121], v[188:191], v[78:81]
	v_mfma_f32_16x16x32_bf16 v[82:85], v[30:33], v[196:199], v[82:85]
	v_mfma_f32_16x16x32_bf16 v[86:89], v[118:121], v[196:199], v[86:89]
	v_mfma_f32_16x16x32_bf16 v[90:93], v[30:33], v[210:213], v[90:93]
	v_mfma_f32_16x16x32_bf16 v[94:97], v[118:121], v[210:213], v[94:97]
	s_setprio 0
	s_setprio 1
	v_mfma_f32_16x16x32_bf16 v[98:101], v[122:125], v[170:173], v[98:101]
	v_mfma_f32_16x16x32_bf16 v[34:37], v[162:165], v[170:173], v[34:37]
	v_mfma_f32_16x16x32_bf16 v[38:41], v[122:125], v[184:187], v[38:41]
	v_mfma_f32_16x16x32_bf16 v[42:45], v[162:165], v[184:187], v[42:45]
	v_mfma_f32_16x16x32_bf16 v[46:49], v[122:125], v[192:195], v[46:49]
	v_mfma_f32_16x16x32_bf16 v[50:53], v[162:165], v[192:195], v[50:53]
	v_mfma_f32_16x16x32_bf16 v[54:57], v[122:125], v[200:203], v[54:57]
	v_mfma_f32_16x16x32_bf16 v[58:61], v[162:165], v[200:203], v[58:61]
	v_mfma_f32_16x16x32_bf16 v[98:101], v[126:129], v[180:183], v[98:101]
	v_mfma_f32_16x16x32_bf16 v[34:37], v[166:169], v[180:183], v[34:37]
	v_mfma_f32_16x16x32_bf16 v[38:41], v[126:129], v[188:191], v[38:41]
	v_mfma_f32_16x16x32_bf16 v[42:45], v[166:169], v[188:191], v[42:45]
	v_mfma_f32_16x16x32_bf16 v[46:49], v[126:129], v[196:199], v[46:49]
	v_mfma_f32_16x16x32_bf16 v[50:53], v[166:169], v[196:199], v[50:53]
	v_mfma_f32_16x16x32_bf16 v[54:57], v[126:129], v[210:213], v[54:57]
	v_mfma_f32_16x16x32_bf16 v[58:61], v[166:169], v[210:213], v[58:61]
	s_setprio 2
	s_barrier
	s_add_i32 s10, s10, s28
	s_mov_b64 s[54:55], 0x180
	s_add_i32 s64, s10, 0x2000
	v_lshl_add_u64 v[174:175], v[174:175], 0, s[54:55]
	s_mov_b32 m0, s10
	s_add_u32 s24, s68, 0x10180
	ds_read_b128 v[170:173], v209 offset:49152
	ds_read_b128 v[180:183], v209 offset:50176
	ds_read_b128 v[184:187], v209 offset:51200
	ds_read_b128 v[188:191], v209 offset:52224
	ds_read_b128 v[192:195], v209 offset:53248
	ds_read_b128 v[196:199], v209 offset:54272
	ds_read_b128 v[200:203], v209 offset:55296
	ds_read_b128 v[210:213], v209 offset:56320
	global_load_lds_dwordx4 v[174:175], off
	v_lshl_add_u64 v[174:175], v[176:177], 0, s[54:55]
	s_mov_b32 m0, s64
	s_addc_u32 s25, s69, 0
	s_add_i32 s16, s16, s28
	global_load_lds_dwordx4 v[174:175], off
	v_lshl_add_u64 v[174:175], s[24:25], 0, v[134:135]
	s_mov_b32 m0, s16
	s_add_i32 s17, s16, 0x2000
	global_load_lds_dwordx4 v[174:175], off
	s_mov_b32 m0, s17
	v_lshl_add_u64 v[174:175], s[24:25], 0, v[130:131]
	global_load_lds_dwordx4 v[174:175], off
	s_mov_b32 m0, s74
	v_lshl_add_u64 v[174:175], v[178:179], 0, s[54:55]
	global_load_lds_dwordx4 v[174:175], off
	s_mov_b32 m0, s75
	v_lshl_add_u64 v[174:175], v[204:205], 0, s[54:55]
	global_load_lds_dwordx4 v[174:175], off
	s_waitcnt vmcnt(8)
	s_waitcnt lgkmcnt(0)
	s_barrier
	s_setprio 1
	s_waitcnt lgkmcnt(0)
	v_mfma_f32_16x16x32_bf16 v[2:5], v[26:29], v[200:203], v[2:5]
	v_mfma_f32_16x16x32_bf16 v[6:9], v[114:117], v[200:203], v[6:9]
	v_mfma_f32_16x16x32_bf16 v[138:141], v[26:29], v[170:173], v[138:141]
	v_mfma_f32_16x16x32_bf16 v[142:145], v[114:117], v[170:173], v[142:145]
	v_mfma_f32_16x16x32_bf16 v[146:149], v[26:29], v[184:187], v[146:149]
	v_mfma_f32_16x16x32_bf16 v[150:153], v[114:117], v[184:187], v[150:153]
	v_mfma_f32_16x16x32_bf16 v[154:157], v[26:29], v[192:195], v[154:157]
	v_mfma_f32_16x16x32_bf16 v[158:161], v[114:117], v[192:195], v[158:161]
	v_mfma_f32_16x16x32_bf16 v[2:5], v[30:33], v[210:213], v[2:5]
	v_mfma_f32_16x16x32_bf16 v[6:9], v[118:121], v[210:213], v[6:9]
	v_mfma_f32_16x16x32_bf16 v[138:141], v[30:33], v[180:183], v[138:141]
	v_mfma_f32_16x16x32_bf16 v[142:145], v[118:121], v[180:183], v[142:145]
	v_mfma_f32_16x16x32_bf16 v[146:149], v[30:33], v[188:191], v[146:149]
	v_mfma_f32_16x16x32_bf16 v[150:153], v[118:121], v[188:191], v[150:153]
	v_mfma_f32_16x16x32_bf16 v[154:157], v[30:33], v[196:199], v[154:157]
	v_mfma_f32_16x16x32_bf16 v[158:161], v[118:121], v[196:199], v[158:161]
	s_setprio 0
	s_setprio 1
	v_mfma_f32_16x16x32_bf16 v[10:13], v[122:125], v[170:173], v[10:13]
	v_mfma_f32_16x16x32_bf16 v[14:17], v[162:165], v[170:173], v[14:17]
	v_mfma_f32_16x16x32_bf16 v[26:29], v[122:125], v[184:187], v[62:65]
	v_mfma_f32_16x16x32_bf16 v[30:33], v[162:165], v[184:187], v[102:105]
	v_mfma_f32_16x16x32_bf16 v[62:65], v[122:125], v[192:195], v[106:109]
	v_mfma_f32_16x16x32_bf16 v[102:105], v[162:165], v[192:195], v[110:113]
	v_mfma_f32_16x16x32_bf16 v[18:21], v[122:125], v[200:203], v[18:21]
	v_mfma_f32_16x16x32_bf16 v[22:25], v[162:165], v[200:203], v[22:25]
	v_mfma_f32_16x16x32_bf16 v[10:13], v[126:129], v[180:183], v[10:13]
	v_mfma_f32_16x16x32_bf16 v[14:17], v[166:169], v[180:183], v[14:17]
	v_mfma_f32_16x16x32_bf16 v[26:29], v[126:129], v[188:191], v[26:29]
	v_mfma_f32_16x16x32_bf16 v[30:33], v[166:169], v[188:191], v[30:33]
	v_mfma_f32_16x16x32_bf16 v[62:65], v[126:129], v[196:199], v[62:65]
	v_mfma_f32_16x16x32_bf16 v[102:105], v[166:169], v[196:199], v[102:105]
	v_mfma_f32_16x16x32_bf16 v[18:21], v[126:129], v[210:213], v[18:21]
	v_mfma_f32_16x16x32_bf16 v[22:25], v[166:169], v[210:213], v[22:25]
	s_setprio 2
	s_barrier
	ds_read_b128 v[106:109], v0
	ds_read_b128 v[110:113], v0 offset:1024
	ds_read_b128 v[114:117], v0 offset:2048
	ds_read_b128 v[118:121], v0 offset:3072
	ds_read_b128 v[122:125], v216
	ds_read_b128 v[126:129], v216 offset:1024
	ds_read_b128 v[162:165], v216 offset:2048
	ds_read_b128 v[166:169], v216 offset:3072
	s_add_u32 s14, s14, 0x100180
	s_addc_u32 s15, s15, 0
	s_mov_b32 m0, s11
	v_lshl_add_u64 v[174:175], s[14:15], 0, v[136:137]
	ds_read_b128 v[170:173], v209
	ds_read_b128 v[180:183], v209 offset:1024
	ds_read_b128 v[184:187], v209 offset:2048
	ds_read_b128 v[188:191], v209 offset:3072
	ds_read_b128 v[192:195], v209 offset:4096
	ds_read_b128 v[196:199], v209 offset:5120
	ds_read_b128 v[200:203], v209 offset:6144
	ds_read_b128 v[210:213], v209 offset:7168
	global_load_lds_dwordx4 v[174:175], off
	s_mov_b32 m0, s45
	v_lshl_add_u64 v[174:175], s[14:15], 0, v[132:133]
	global_load_lds_dwordx4 v[174:175], off
	s_waitcnt vmcnt(8)
	s_waitcnt lgkmcnt(0)
	s_barrier
	s_setprio 1
	s_waitcnt lgkmcnt(0)
	v_mfma_f32_16x16x32_bf16 v[66:69], v[106:109], v[170:173], v[66:69]
	v_mfma_f32_16x16x32_bf16 v[70:73], v[114:117], v[170:173], v[70:73]
	v_mfma_f32_16x16x32_bf16 v[74:77], v[106:109], v[184:187], v[74:77]
	v_mfma_f32_16x16x32_bf16 v[78:81], v[114:117], v[184:187], v[78:81]
	v_mfma_f32_16x16x32_bf16 v[82:85], v[106:109], v[192:195], v[82:85]
	v_mfma_f32_16x16x32_bf16 v[86:89], v[114:117], v[192:195], v[86:89]
	v_mfma_f32_16x16x32_bf16 v[90:93], v[106:109], v[200:203], v[90:93]
	v_mfma_f32_16x16x32_bf16 v[66:69], v[110:113], v[180:183], v[66:69]
	v_mfma_f32_16x16x32_bf16 v[70:73], v[118:121], v[180:183], v[70:73]
	v_mfma_f32_16x16x32_bf16 v[74:77], v[110:113], v[188:191], v[74:77]
	v_mfma_f32_16x16x32_bf16 v[78:81], v[118:121], v[188:191], v[78:81]
	v_mfma_f32_16x16x32_bf16 v[82:85], v[110:113], v[196:199], v[82:85]
	v_mfma_f32_16x16x32_bf16 v[86:89], v[118:121], v[196:199], v[86:89]
	v_mfma_f32_16x16x32_bf16 v[90:93], v[110:113], v[210:213], v[90:93]
	v_mfma_f32_16x16x32_bf16 v[94:97], v[114:117], v[200:203], v[94:97]
	v_mfma_f32_16x16x32_bf16 v[214:217], v[118:121], v[210:213], v[94:97]
	s_setprio 0
	s_setprio 1
	v_mfma_f32_16x16x32_bf16 v[94:97], v[122:125], v[170:173], v[98:101]
	v_mfma_f32_16x16x32_bf16 v[34:37], v[162:165], v[170:173], v[34:37]
	v_mfma_f32_16x16x32_bf16 v[38:41], v[122:125], v[184:187], v[38:41]
	v_mfma_f32_16x16x32_bf16 v[42:45], v[162:165], v[184:187], v[42:45]
	v_mfma_f32_16x16x32_bf16 v[46:49], v[122:125], v[192:195], v[46:49]
	v_mfma_f32_16x16x32_bf16 v[50:53], v[162:165], v[192:195], v[50:53]
	v_mfma_f32_16x16x32_bf16 v[54:57], v[122:125], v[200:203], v[54:57]
	v_mfma_f32_16x16x32_bf16 v[58:61], v[162:165], v[200:203], v[58:61]
	v_mfma_f32_16x16x32_bf16 v[98:101], v[126:129], v[180:183], v[94:97]
	v_mfma_f32_16x16x32_bf16 v[34:37], v[166:169], v[180:183], v[34:37]
	v_mfma_f32_16x16x32_bf16 v[38:41], v[126:129], v[188:191], v[38:41]
	v_mfma_f32_16x16x32_bf16 v[42:45], v[166:169], v[188:191], v[42:45]
	v_mfma_f32_16x16x32_bf16 v[46:49], v[126:129], v[196:199], v[46:49]
	v_mfma_f32_16x16x32_bf16 v[50:53], v[166:169], v[196:199], v[50:53]
	v_mfma_f32_16x16x32_bf16 v[54:57], v[126:129], v[210:213], v[54:57]
	v_mfma_f32_16x16x32_bf16 v[58:61], v[166:169], v[210:213], v[58:61]
	s_setprio 2
	s_barrier
	s_mov_b32 m0, vcc_hi
	v_lshl_add_u64 v[178:179], s[70:71], 0, v[134:135]
	s_add_u32 s14, s70, 0x10000
	ds_read_b128 v[94:97], v209 offset:16384
	ds_read_b128 v[170:173], v209 offset:17408
	ds_read_b128 v[180:183], v209 offset:18432
	ds_read_b128 v[184:187], v209 offset:19456
	ds_read_b128 v[188:191], v209 offset:20480
	ds_read_b128 v[192:195], v209 offset:21504
	ds_read_b128 v[196:199], v209 offset:22528
	ds_read_b128 v[200:203], v209 offset:23552
	global_load_lds_dwordx4 v[178:179], off
	v_lshl_add_u64 v[204:205], s[70:71], 0, v[130:131]
	s_mov_b32 m0, s57
	s_addc_u32 s15, s71, 0
	global_load_lds_dwordx4 v[204:205], off
	v_lshl_add_u64 v[174:175], s[14:15], 0, v[134:135]
	s_mov_b32 m0, s91
	v_lshl_add_u64 v[230:231], s[72:73], 0, v[136:137]
	global_load_lds_dwordx4 v[174:175], off
	v_lshl_add_u64 v[174:175], s[14:15], 0, v[130:131]
	s_mov_b32 m0, vcc_lo
	v_lshl_add_u64 v[234:235], s[72:73], 0, v[132:133]
	global_load_lds_dwordx4 v[174:175], off
	s_mov_b32 m0, s40
	s_nop 0
	global_load_lds_dwordx4 v[230:231], off
	s_mov_b32 m0, s41
	s_nop 0
	global_load_lds_dwordx4 v[234:235], off
	s_waitcnt vmcnt(8)
	s_waitcnt lgkmcnt(0)
	s_barrier
	s_setprio 1
	s_waitcnt lgkmcnt(0)
	v_mfma_f32_16x16x32_bf16 v[2:5], v[106:109], v[196:199], v[2:5]
	v_mfma_f32_16x16x32_bf16 v[138:141], v[106:109], v[94:97], v[138:141]
	v_mfma_f32_16x16x32_bf16 v[142:145], v[114:117], v[94:97], v[142:145]
	v_mfma_f32_16x16x32_bf16 v[146:149], v[106:109], v[180:183], v[146:149]
	v_mfma_f32_16x16x32_bf16 v[150:153], v[114:117], v[180:183], v[150:153]
	v_mfma_f32_16x16x32_bf16 v[154:157], v[106:109], v[188:191], v[154:157]
	v_mfma_f32_16x16x32_bf16 v[158:161], v[114:117], v[188:191], v[158:161]
	v_mfma_f32_16x16x32_bf16 v[210:213], v[110:113], v[200:203], v[2:5]
	v_mfma_f32_16x16x32_bf16 v[2:5], v[114:117], v[196:199], v[6:9]
	v_mfma_f32_16x16x32_bf16 v[138:141], v[110:113], v[170:173], v[138:141]
	v_mfma_f32_16x16x32_bf16 v[142:145], v[118:121], v[170:173], v[142:145]
	v_mfma_f32_16x16x32_bf16 v[146:149], v[110:113], v[184:187], v[146:149]
	v_mfma_f32_16x16x32_bf16 v[150:153], v[118:121], v[184:187], v[150:153]
	v_mfma_f32_16x16x32_bf16 v[154:157], v[110:113], v[192:195], v[154:157]
	v_mfma_f32_16x16x32_bf16 v[158:161], v[118:121], v[192:195], v[158:161]
	v_mfma_f32_16x16x32_bf16 v[218:221], v[118:121], v[200:203], v[2:5]
	s_setprio 0
	s_setprio 1
	v_mfma_f32_16x16x32_bf16 v[2:5], v[122:125], v[94:97], v[10:13]
	v_mfma_f32_16x16x32_bf16 v[222:225], v[126:129], v[170:173], v[2:5]
	v_mfma_f32_16x16x32_bf16 v[2:5], v[162:165], v[94:97], v[14:17]
	v_mfma_f32_16x16x32_bf16 v[170:173], v[166:169], v[170:173], v[2:5]
	v_mfma_f32_16x16x32_bf16 v[2:5], v[122:125], v[180:183], v[26:29]
	v_mfma_f32_16x16x32_bf16 v[250:253], v[126:129], v[184:187], v[2:5]
	v_mfma_f32_16x16x32_bf16 v[2:5], v[162:165], v[180:183], v[30:33]
	v_mfma_f32_16x16x32_bf16 v[180:183], v[166:169], v[184:187], v[2:5]
	v_mfma_f32_16x16x32_bf16 v[2:5], v[122:125], v[188:191], v[62:65]
	v_mfma_f32_16x16x32_bf16 v[62:65], v[126:129], v[192:195], v[2:5]
	v_mfma_f32_16x16x32_bf16 v[2:5], v[162:165], v[188:191], v[102:105]
	v_mfma_f32_16x16x32_bf16 v[184:187], v[166:169], v[192:195], v[2:5]
	v_mfma_f32_16x16x32_bf16 v[2:5], v[122:125], v[196:199], v[18:21]
	v_mfma_f32_16x16x32_bf16 v[188:191], v[126:129], v[200:203], v[2:5]
	v_mfma_f32_16x16x32_bf16 v[2:5], v[162:165], v[196:199], v[22:25]
	v_mfma_f32_16x16x32_bf16 v[162:165], v[166:169], v[200:203], v[2:5]
	s_setprio 2
	s_barrier
	ds_read_b128 v[166:169], v226
	ds_read_b128 v[192:195], v226 offset:1024
	ds_read_b128 v[196:199], v226 offset:2048
	ds_read_b128 v[200:203], v226 offset:3072
	ds_read_b128 v[238:241], v227
	ds_read_b128 v[242:245], v227 offset:1024
	ds_read_b128 v[246:249], v227 offset:2048
	ds_read_b128 v[226:229], v227 offset:3072
	s_add_u32 s14, s72, 0x100000
	s_addc_u32 s15, s73, 0
	s_mov_b32 m0, s48
	v_lshl_add_u64 v[2:3], s[14:15], 0, v[136:137]
	ds_read_b128 v[6:9], v209 offset:32768
	ds_read_b128 v[10:13], v209 offset:33792
	ds_read_b128 v[14:17], v209 offset:34816
	ds_read_b128 v[18:21], v209 offset:35840
	ds_read_b128 v[22:25], v209 offset:36864
	ds_read_b128 v[26:29], v209 offset:37888
	ds_read_b128 v[30:33], v209 offset:38912
	ds_read_b128 v[102:105], v209 offset:39936
	global_load_lds_dwordx4 v[2:3], off
	s_mov_b32 m0, s52
	v_lshl_add_u64 v[2:3], s[14:15], 0, v[132:133]
	global_load_lds_dwordx4 v[2:3], off
	s_waitcnt vmcnt(8)
	s_waitcnt lgkmcnt(0)
	s_barrier
	s_setprio 1
	s_waitcnt lgkmcnt(0)
	v_mfma_f32_16x16x32_bf16 v[2:5], v[166:169], v[6:9], v[66:69]
	v_mfma_f32_16x16x32_bf16 v[126:129], v[192:195], v[10:13], v[2:5]
	v_mfma_f32_16x16x32_bf16 v[2:5], v[196:199], v[6:9], v[70:73]
	v_mfma_f32_16x16x32_bf16 v[122:125], v[200:203], v[10:13], v[2:5]
	v_mfma_f32_16x16x32_bf16 v[2:5], v[166:169], v[14:17], v[74:77]
	v_mfma_f32_16x16x32_bf16 v[118:121], v[192:195], v[18:21], v[2:5]
	v_mfma_f32_16x16x32_bf16 v[2:5], v[196:199], v[14:17], v[78:81]
	v_mfma_f32_16x16x32_bf16 v[114:117], v[200:203], v[18:21], v[2:5]
	v_mfma_f32_16x16x32_bf16 v[2:5], v[166:169], v[22:25], v[82:85]
	v_mfma_f32_16x16x32_bf16 v[110:113], v[192:195], v[26:29], v[2:5]
	v_mfma_f32_16x16x32_bf16 v[2:5], v[196:199], v[22:25], v[86:89]
	v_mfma_f32_16x16x32_bf16 v[106:109], v[200:203], v[26:29], v[2:5]
	v_mfma_f32_16x16x32_bf16 v[2:5], v[166:169], v[30:33], v[90:93]
	v_mfma_f32_16x16x32_bf16 v[94:97], v[192:195], v[102:105], v[2:5]
	v_mfma_f32_16x16x32_bf16 v[2:5], v[196:199], v[30:33], v[214:217]
	v_mfma_f32_16x16x32_bf16 v[90:93], v[200:203], v[102:105], v[2:5]
	s_setprio 0
	s_setprio 1
	v_mfma_f32_16x16x32_bf16 v[2:5], v[238:241], v[6:9], v[98:101]
	v_mfma_f32_16x16x32_bf16 v[6:9], v[246:249], v[6:9], v[34:37]
	v_mfma_f32_16x16x32_bf16 v[2:5], v[242:245], v[10:13], v[2:5]
	v_mfma_f32_16x16x32_bf16 v[6:9], v[226:229], v[10:13], v[6:9]
	v_mfma_f32_16x16x32_bf16 v[10:13], v[238:241], v[14:17], v[38:41]
	v_mfma_f32_16x16x32_bf16 v[14:17], v[246:249], v[14:17], v[42:45]
	v_mfma_f32_16x16x32_bf16 v[10:13], v[242:245], v[18:21], v[10:13]
	v_mfma_f32_16x16x32_bf16 v[14:17], v[226:229], v[18:21], v[14:17]
	v_mfma_f32_16x16x32_bf16 v[18:21], v[238:241], v[22:25], v[46:49]
	v_mfma_f32_16x16x32_bf16 v[22:25], v[246:249], v[22:25], v[50:53]
	v_mfma_f32_16x16x32_bf16 v[18:21], v[242:245], v[26:29], v[18:21]
	v_mfma_f32_16x16x32_bf16 v[22:25], v[226:229], v[26:29], v[22:25]
	v_mfma_f32_16x16x32_bf16 v[26:29], v[238:241], v[30:33], v[54:57]
	v_mfma_f32_16x16x32_bf16 v[30:33], v[246:249], v[30:33], v[58:61]
	v_mfma_f32_16x16x32_bf16 v[26:29], v[242:245], v[102:105], v[26:29]
	v_mfma_f32_16x16x32_bf16 v[30:33], v[226:229], v[102:105], v[30:33]
	s_setprio 2
	s_barrier
	s_mov_b32 m0, s10
	v_lshl_add_u64 v[34:35], v[178:179], 0, s[94:95]
	s_add_u32 s10, s70, 0x10080
	ds_read_b128 v[38:41], v209 offset:49152
	ds_read_b128 v[42:45], v209 offset:50176
	ds_read_b128 v[46:49], v209 offset:51200
	ds_read_b128 v[50:53], v209 offset:52224
	ds_read_b128 v[54:57], v209 offset:53248
	ds_read_b128 v[58:61], v209 offset:54272
	ds_read_b128 v[214:217], v209 offset:55296
	ds_read_b128 v[174:177], v209 offset:56320
	global_load_lds_dwordx4 v[34:35], off
	v_lshl_add_u64 v[34:35], v[204:205], 0, s[94:95]
	s_mov_b32 m0, s64
	s_addc_u32 s11, s71, 0
	global_load_lds_dwordx4 v[34:35], off
	s_mov_b32 m0, s16
	v_lshl_add_u64 v[34:35], s[10:11], 0, v[134:135]
	global_load_lds_dwordx4 v[34:35], off
	s_mov_b32 m0, s17
	v_lshl_add_u64 v[34:35], s[10:11], 0, v[130:131]
	global_load_lds_dwordx4 v[34:35], off
	s_mov_b32 m0, s74
	v_lshl_add_u64 v[34:35], v[230:231], 0, s[94:95]
	global_load_lds_dwordx4 v[34:35], off
	s_mov_b32 m0, s75
	v_lshl_add_u64 v[34:35], v[234:235], 0, s[94:95]
	global_load_lds_dwordx4 v[34:35], off
	s_waitcnt vmcnt(8)
	s_waitcnt lgkmcnt(0)
	s_barrier
	s_setprio 1
	s_waitcnt lgkmcnt(0)
	v_mfma_f32_16x16x32_bf16 v[34:37], v[166:169], v[38:41], v[138:141]
	v_mfma_f32_16x16x32_bf16 v[102:105], v[192:195], v[42:45], v[34:37]
	v_mfma_f32_16x16x32_bf16 v[34:37], v[196:199], v[38:41], v[142:145]
	v_mfma_f32_16x16x32_bf16 v[98:101], v[200:203], v[42:45], v[34:37]
	v_mfma_f32_16x16x32_bf16 v[34:37], v[166:169], v[46:49], v[146:149]
	v_mfma_f32_16x16x32_bf16 v[86:89], v[192:195], v[50:53], v[34:37]
	v_mfma_f32_16x16x32_bf16 v[34:37], v[196:199], v[46:49], v[150:153]
	v_mfma_f32_16x16x32_bf16 v[82:85], v[200:203], v[50:53], v[34:37]
	v_mfma_f32_16x16x32_bf16 v[34:37], v[166:169], v[54:57], v[154:157]
	v_mfma_f32_16x16x32_bf16 v[78:81], v[192:195], v[58:61], v[34:37]
	v_mfma_f32_16x16x32_bf16 v[34:37], v[196:199], v[54:57], v[158:161]
	v_mfma_f32_16x16x32_bf16 v[74:77], v[200:203], v[58:61], v[34:37]
	v_mfma_f32_16x16x32_bf16 v[34:37], v[166:169], v[214:217], v[210:213]
	v_mfma_f32_16x16x32_bf16 v[70:73], v[192:195], v[174:177], v[34:37]
	v_mfma_f32_16x16x32_bf16 v[34:37], v[196:199], v[214:217], v[218:221]
	v_mfma_f32_16x16x32_bf16 v[66:69], v[200:203], v[174:177], v[34:37]
	s_setprio 0
	s_setprio 1
	v_mfma_f32_16x16x32_bf16 v[34:37], v[238:241], v[38:41], v[222:225]
	v_mfma_f32_16x16x32_bf16 v[38:41], v[246:249], v[38:41], v[170:173]
	v_mfma_f32_16x16x32_bf16 v[34:37], v[242:245], v[42:45], v[34:37]
	v_mfma_f32_16x16x32_bf16 v[38:41], v[226:229], v[42:45], v[38:41]
	v_mfma_f32_16x16x32_bf16 v[42:45], v[238:241], v[46:49], v[250:253]
	v_mfma_f32_16x16x32_bf16 v[46:49], v[246:249], v[46:49], v[180:183]
	v_mfma_f32_16x16x32_bf16 v[42:45], v[242:245], v[50:53], v[42:45]
	v_mfma_f32_16x16x32_bf16 v[46:49], v[226:229], v[50:53], v[46:49]
	v_mfma_f32_16x16x32_bf16 v[50:53], v[238:241], v[54:57], v[62:65]
	v_mfma_f32_16x16x32_bf16 v[54:57], v[246:249], v[54:57], v[184:187]
	v_mfma_f32_16x16x32_bf16 v[50:53], v[242:245], v[58:61], v[50:53]
	v_mfma_f32_16x16x32_bf16 v[54:57], v[226:229], v[58:61], v[54:57]
	v_mfma_f32_16x16x32_bf16 v[58:61], v[238:241], v[214:217], v[188:191]
	v_mfma_f32_16x16x32_bf16 v[62:65], v[246:249], v[214:217], v[162:165]
	v_mfma_f32_16x16x32_bf16 v[58:61], v[242:245], v[174:177], v[58:61]
	v_mfma_f32_16x16x32_bf16 v[62:65], v[226:229], v[174:177], v[62:65]
	s_setprio 2
	s_barrier
	s_andn2_b64 vcc, exec, s[38:39]
	s_cbranch_vccnz .LBB0_362
	s_barrier

.Lat1_skip:
	s_and_b64 vcc, exec, s[22:23]
	s_cbranch_vccnz .Lat1_skip_nodma
	v_mad_u64_u32 v[202:203], s[10:11], s86, v228, v[180:181]
	s_mul_i32 s10, s7, 0xa000
	s_add_i32 s10, s9, s10
	s_mov_b32 m0, s10
	v_lshl_add_u64 v[204:205], v[202:203], 0, s[94:95]
	global_load_lds_dwordx4 v[202:203], off
	s_add_i32 m0, s10, 0x2000
	v_lshl_add_u64 v[202:203], v[202:203], 0, s[96:97]
	global_load_lds_dwordx4 v[204:205], off
	s_add_i32 m0, s10, 0x4000
	s_nop 0
	global_load_lds_dwordx4 v[202:203], off
	s_add_i32 m0, s10, 0x6000
	v_lshl_add_u64 v[202:203], s[86:87], 1, v[182:183]
	global_load_lds_dwordx4 v[202:203], off
	s_add_i32 m0, s10, 0x8000
	v_lshl_add_u64 v[202:203], v[202:203], 0, s[92:93]
	global_load_lds_dwordx4 v[202:203], off
	s_waitcnt vmcnt(5) lgkmcnt(0)
	s_branch .LBB0_530

.Lat2_skip:
	s_and_b64 vcc, exec, s[22:23]
	s_cbranch_vccnz .Lat2_skip_nodma
	v_mad_u64_u32 v[204:205], s[10:11], s86, v228, v[174:175]
	s_mul_i32 s10, s7, 0xa000
	s_add_i32 s10, s0, s10
	s_mov_b32 m0, s10
	v_lshl_add_u64 v[206:207], v[204:205], 0, s[94:95]
	global_load_lds_dwordx4 v[204:205], off
	s_add_i32 m0, s10, 0x2000
	v_lshl_add_u64 v[204:205], v[204:205], 0, s[96:97]
	global_load_lds_dwordx4 v[206:207], off
	s_add_i32 m0, s10, 0x4000
	s_nop 0
	global_load_lds_dwordx4 v[204:205], off
	s_add_i32 m0, s10, 0x6000
	v_lshl_add_u64 v[204:205], s[86:87], 1, v[180:181]
	global_load_lds_dwordx4 v[204:205], off
	s_add_i32 m0, s10, 0x8000
	v_lshl_add_u64 v[204:205], v[204:205], 0, s[92:93]
	global_load_lds_dwordx4 v[204:205], off
	s_waitcnt vmcnt(5) lgkmcnt(0)
	s_branch .LBB0_573

.LBB0_685:
	s_add_u32 s36, s12, s38
	s_addc_u32 s42, s13, s39
	s_add_u32 s36, s36, 0x100
	s_addc_u32 s42, s42, 0
	s_add_u32 s62, s35, s38
	s_addc_u32 s43, s63, s39
	s_cmpk_eq_i32 s38, 0xf00
	s_cselect_b32 s45, s27, s42
	s_cselect_b32 s44, s60, s36
	s_cselect_b32 s43, s21, s43
	s_cselect_b32 s42, s61, s62
	s_add_i32 s36, 0, 0x10000
	v_add_u32_e32 v0, s36, v188
	s_add_i32 s62, 0, 0x14000
	ds_read_b128 v[138:141], v0
	ds_read_b128 v[142:145], v0 offset:1024
	ds_read_b128 v[146:149], v0 offset:2048
	ds_read_b128 v[150:153], v0 offset:3072
	v_add_u32_e32 v0, s62, v188
	ds_read_b128 v[170:173], v0
	ds_read_b128 v[174:177], v0 offset:1024
	ds_read_b128 v[178:181], v0 offset:2048
	ds_read_b128 v[182:185], v0 offset:3072
	v_lshl_add_u64 v[2:3], v[136:137], 0, s[38:39]
	s_add_i32 m0, s33, 0xc000
	ds_read_b128 v[190:193], v189
	ds_read_b128 v[194:197], v189 offset:1024
	ds_read_b128 v[198:201], v189 offset:2048
	ds_read_b128 v[202:205], v189 offset:3072
	ds_read_b128 v[206:209], v189 offset:4096
	ds_read_b128 v[210:213], v189 offset:5120
	ds_read_b128 v[214:217], v189 offset:6144
	ds_read_b128 v[218:221], v189 offset:7168
	global_load_lds_dwordx4 v[2:3], off
	s_add_i32 m0, s33, 0xe000
	v_lshl_add_u64 v[2:3], v[134:135], 0, s[38:39]
	global_load_lds_dwordx4 v[2:3], off
	s_waitcnt vmcnt(8)
	s_waitcnt lgkmcnt(0)
	s_barrier
	s_setprio 1
	s_waitcnt lgkmcnt(0)
	v_mfma_f32_16x16x32_bf16 v[128:131], v[138:141], v[190:193], v[128:131]
	v_mfma_f32_16x16x32_bf16 v[124:127], v[146:149], v[190:193], v[124:127]
	v_mfma_f32_16x16x32_bf16 v[112:115], v[138:141], v[198:201], v[112:115]
	v_mfma_f32_16x16x32_bf16 v[108:111], v[146:149], v[198:201], v[108:111]
	v_mfma_f32_16x16x32_bf16 v[96:99], v[138:141], v[206:209], v[96:99]
	v_mfma_f32_16x16x32_bf16 v[92:95], v[146:149], v[206:209], v[92:95]
	v_mfma_f32_16x16x32_bf16 v[80:83], v[138:141], v[214:217], v[80:83]
	v_mfma_f32_16x16x32_bf16 v[76:79], v[146:149], v[214:217], v[76:79]
	v_mfma_f32_16x16x32_bf16 v[128:131], v[142:145], v[194:197], v[128:131]
	v_mfma_f32_16x16x32_bf16 v[124:127], v[150:153], v[194:197], v[124:127]
	v_mfma_f32_16x16x32_bf16 v[112:115], v[142:145], v[202:205], v[112:115]
	v_mfma_f32_16x16x32_bf16 v[108:111], v[150:153], v[202:205], v[108:111]
	v_mfma_f32_16x16x32_bf16 v[96:99], v[142:145], v[210:213], v[96:99]
	v_mfma_f32_16x16x32_bf16 v[92:95], v[150:153], v[210:213], v[92:95]
	v_mfma_f32_16x16x32_bf16 v[80:83], v[142:145], v[218:221], v[80:83]
	v_mfma_f32_16x16x32_bf16 v[76:79], v[150:153], v[218:221], v[76:79]
	s_setprio 0
	s_setprio 1
	v_mfma_f32_16x16x32_bf16 v[120:123], v[170:173], v[190:193], v[120:123]
	v_mfma_f32_16x16x32_bf16 v[116:119], v[178:181], v[190:193], v[116:119]
	v_mfma_f32_16x16x32_bf16 v[104:107], v[170:173], v[198:201], v[104:107]
	v_mfma_f32_16x16x32_bf16 v[100:103], v[178:181], v[198:201], v[100:103]
	v_mfma_f32_16x16x32_bf16 v[88:91], v[170:173], v[206:209], v[88:91]
	v_mfma_f32_16x16x32_bf16 v[84:87], v[178:181], v[206:209], v[84:87]
	v_mfma_f32_16x16x32_bf16 v[72:75], v[170:173], v[214:217], v[72:75]
	v_mfma_f32_16x16x32_bf16 v[68:71], v[178:181], v[214:217], v[68:71]
	v_mfma_f32_16x16x32_bf16 v[120:123], v[174:177], v[194:197], v[120:123]
	v_mfma_f32_16x16x32_bf16 v[116:119], v[182:185], v[194:197], v[116:119]
	v_mfma_f32_16x16x32_bf16 v[104:107], v[174:177], v[202:205], v[104:107]
	v_mfma_f32_16x16x32_bf16 v[100:103], v[182:185], v[202:205], v[100:103]
	v_mfma_f32_16x16x32_bf16 v[88:91], v[174:177], v[210:213], v[88:91]
	v_mfma_f32_16x16x32_bf16 v[84:87], v[182:185], v[210:213], v[84:87]
	v_mfma_f32_16x16x32_bf16 v[72:75], v[174:177], v[218:221], v[72:75]
	v_mfma_f32_16x16x32_bf16 v[68:71], v[182:185], v[218:221], v[68:71]
	s_setprio 2
	s_barrier
	s_add_i32 s36, s36, s41
	v_lshl_add_u64 v[154:155], s[42:43], 0, v[160:161]
	s_mov_b32 m0, s36
	ds_read_b128 v[190:193], v189 offset:16384
	ds_read_b128 v[194:197], v189 offset:17408
	ds_read_b128 v[198:201], v189 offset:18432
	ds_read_b128 v[202:205], v189 offset:19456
	ds_read_b128 v[206:209], v189 offset:20480
	ds_read_b128 v[210:213], v189 offset:21504
	ds_read_b128 v[214:217], v189 offset:22528
	ds_read_b128 v[218:221], v189 offset:23552
	global_load_lds_dwordx4 v[154:155], off
	s_add_i32 m0, s36, 0x2000
	s_add_u32 s66, s42, 0x80000
	v_lshl_add_u64 v[222:223], s[42:43], 0, v[156:157]
	s_addc_u32 s67, s43, 0
	s_add_i32 s36, s62, s41
	global_load_lds_dwordx4 v[222:223], off
	v_lshl_add_u64 v[2:3], s[66:67], 0, v[160:161]
	s_mov_b32 m0, s36
	v_lshl_add_u64 v[224:225], s[44:45], 0, v[162:163]
	global_load_lds_dwordx4 v[2:3], off
	v_lshl_add_u64 v[2:3], s[66:67], 0, v[156:157]
	s_add_i32 m0, s36, 0x2000
	v_lshl_add_u64 v[226:227], s[44:45], 0, v[158:159]
	global_load_lds_dwordx4 v[2:3], off
	s_mov_b32 m0, s33
	s_nop 0
	global_load_lds_dwordx4 v[224:225], off
	s_mov_b32 m0, s56
	s_nop 0
	global_load_lds_dwordx4 v[226:227], off
	s_waitcnt vmcnt(8)
	s_waitcnt lgkmcnt(0)
	s_barrier
	s_setprio 1
	s_waitcnt lgkmcnt(0)
	v_mfma_f32_16x16x32_bf16 v[64:67], v[138:141], v[190:193], v[64:67]
	v_mfma_f32_16x16x32_bf16 v[60:63], v[146:149], v[190:193], v[60:63]
	v_mfma_f32_16x16x32_bf16 v[48:51], v[138:141], v[198:201], v[48:51]
	v_mfma_f32_16x16x32_bf16 v[44:47], v[146:149], v[198:201], v[44:47]
	v_mfma_f32_16x16x32_bf16 v[32:35], v[138:141], v[206:209], v[32:35]
	v_mfma_f32_16x16x32_bf16 v[28:31], v[146:149], v[206:209], v[28:31]
	v_mfma_f32_16x16x32_bf16 v[16:19], v[138:141], v[214:217], v[16:19]
	v_mfma_f32_16x16x32_bf16 v[12:15], v[146:149], v[214:217], v[12:15]
	v_mfma_f32_16x16x32_bf16 v[64:67], v[142:145], v[194:197], v[64:67]
	v_mfma_f32_16x16x32_bf16 v[60:63], v[150:153], v[194:197], v[60:63]
	v_mfma_f32_16x16x32_bf16 v[48:51], v[142:145], v[202:205], v[48:51]
	v_mfma_f32_16x16x32_bf16 v[44:47], v[150:153], v[202:205], v[44:47]
	v_mfma_f32_16x16x32_bf16 v[32:35], v[142:145], v[210:213], v[32:35]
	v_mfma_f32_16x16x32_bf16 v[28:31], v[150:153], v[210:213], v[28:31]
	v_mfma_f32_16x16x32_bf16 v[16:19], v[142:145], v[218:221], v[16:19]
	v_mfma_f32_16x16x32_bf16 v[12:15], v[150:153], v[218:221], v[12:15]
	s_setprio 0
	s_setprio 1
	v_mfma_f32_16x16x32_bf16 v[56:59], v[170:173], v[190:193], v[56:59]
	v_mfma_f32_16x16x32_bf16 v[52:55], v[178:181], v[190:193], v[52:55]
	v_mfma_f32_16x16x32_bf16 v[40:43], v[170:173], v[198:201], v[40:43]
	v_mfma_f32_16x16x32_bf16 v[36:39], v[178:181], v[198:201], v[36:39]
	v_mfma_f32_16x16x32_bf16 v[24:27], v[170:173], v[206:209], v[24:27]
	v_mfma_f32_16x16x32_bf16 v[20:23], v[178:181], v[206:209], v[20:23]
	v_mfma_f32_16x16x32_bf16 v[8:11], v[170:173], v[214:217], v[8:11]
	v_mfma_f32_16x16x32_bf16 v[2:5], v[178:181], v[214:217], v[4:7]
	v_mfma_f32_16x16x32_bf16 v[56:59], v[174:177], v[194:197], v[56:59]
	v_mfma_f32_16x16x32_bf16 v[52:55], v[182:185], v[194:197], v[52:55]
	v_mfma_f32_16x16x32_bf16 v[40:43], v[174:177], v[202:205], v[40:43]
	v_mfma_f32_16x16x32_bf16 v[36:39], v[182:185], v[202:205], v[36:39]
	v_mfma_f32_16x16x32_bf16 v[24:27], v[174:177], v[210:213], v[24:27]
	v_mfma_f32_16x16x32_bf16 v[20:23], v[182:185], v[210:213], v[20:23]
	v_mfma_f32_16x16x32_bf16 v[8:11], v[174:177], v[218:221], v[8:11]
	v_mfma_f32_16x16x32_bf16 v[2:5], v[182:185], v[218:221], v[2:5]
	s_setprio 2
	s_barrier
	s_add_i32 s36, 0, 0x18000
	v_add_u32_e32 v0, s36, v188
	s_add_i32 s62, 0, 0x1c000
	ds_read_b128 v[138:141], v0
	ds_read_b128 v[142:145], v0 offset:1024
	ds_read_b128 v[146:149], v0 offset:2048
	ds_read_b128 v[150:153], v0 offset:3072
	v_add_u32_e32 v0, s62, v188
	ds_read_b128 v[170:173], v0
	ds_read_b128 v[174:177], v0 offset:1024
	ds_read_b128 v[178:181], v0 offset:2048
	ds_read_b128 v[182:185], v0 offset:3072
	s_add_u32 s44, s44, 0x80000
	s_addc_u32 s45, s45, 0
	s_mov_b32 m0, s57
	v_lshl_add_u64 v[6:7], s[44:45], 0, v[162:163]
	ds_read_b128 v[190:193], v189 offset:32768
	ds_read_b128 v[194:197], v189 offset:33792
	ds_read_b128 v[198:201], v189 offset:34816
	ds_read_b128 v[202:205], v189 offset:35840
	ds_read_b128 v[206:209], v189 offset:36864
	ds_read_b128 v[210:213], v189 offset:37888
	ds_read_b128 v[214:217], v189 offset:38912
	ds_read_b128 v[218:221], v189 offset:39936
	global_load_lds_dwordx4 v[6:7], off
	s_mov_b32 m0, s59
	v_lshl_add_u64 v[6:7], s[44:45], 0, v[158:159]
	global_load_lds_dwordx4 v[6:7], off
	s_waitcnt vmcnt(8)
	s_waitcnt lgkmcnt(0)
	s_barrier
	s_setprio 1
	s_waitcnt lgkmcnt(0)
	v_mfma_f32_16x16x32_bf16 v[128:131], v[138:141], v[190:193], v[128:131]
	v_mfma_f32_16x16x32_bf16 v[124:127], v[146:149], v[190:193], v[124:127]
	v_mfma_f32_16x16x32_bf16 v[112:115], v[138:141], v[198:201], v[112:115]
	v_mfma_f32_16x16x32_bf16 v[108:111], v[146:149], v[198:201], v[108:111]
	v_mfma_f32_16x16x32_bf16 v[96:99], v[138:141], v[206:209], v[96:99]
	v_mfma_f32_16x16x32_bf16 v[92:95], v[146:149], v[206:209], v[92:95]
	v_mfma_f32_16x16x32_bf16 v[80:83], v[138:141], v[214:217], v[80:83]
	v_mfma_f32_16x16x32_bf16 v[76:79], v[146:149], v[214:217], v[76:79]
	v_mfma_f32_16x16x32_bf16 v[128:131], v[142:145], v[194:197], v[128:131]
	v_mfma_f32_16x16x32_bf16 v[124:127], v[150:153], v[194:197], v[124:127]
	v_mfma_f32_16x16x32_bf16 v[112:115], v[142:145], v[202:205], v[112:115]
	v_mfma_f32_16x16x32_bf16 v[108:111], v[150:153], v[202:205], v[108:111]
	v_mfma_f32_16x16x32_bf16 v[96:99], v[142:145], v[210:213], v[96:99]
	v_mfma_f32_16x16x32_bf16 v[92:95], v[150:153], v[210:213], v[92:95]
	v_mfma_f32_16x16x32_bf16 v[80:83], v[142:145], v[218:221], v[80:83]
	v_mfma_f32_16x16x32_bf16 v[76:79], v[150:153], v[218:221], v[76:79]
	s_setprio 0
	s_setprio 1
	v_mfma_f32_16x16x32_bf16 v[120:123], v[170:173], v[190:193], v[120:123]
	v_mfma_f32_16x16x32_bf16 v[116:119], v[178:181], v[190:193], v[116:119]
	v_mfma_f32_16x16x32_bf16 v[104:107], v[170:173], v[198:201], v[104:107]
	v_mfma_f32_16x16x32_bf16 v[100:103], v[178:181], v[198:201], v[100:103]
	v_mfma_f32_16x16x32_bf16 v[88:91], v[170:173], v[206:209], v[88:91]
	v_mfma_f32_16x16x32_bf16 v[84:87], v[178:181], v[206:209], v[84:87]
	v_mfma_f32_16x16x32_bf16 v[72:75], v[170:173], v[214:217], v[72:75]
	v_mfma_f32_16x16x32_bf16 v[68:71], v[178:181], v[214:217], v[68:71]
	v_mfma_f32_16x16x32_bf16 v[120:123], v[174:177], v[194:197], v[120:123]
	v_mfma_f32_16x16x32_bf16 v[116:119], v[182:185], v[194:197], v[116:119]
	v_mfma_f32_16x16x32_bf16 v[104:107], v[174:177], v[202:205], v[104:107]
	v_mfma_f32_16x16x32_bf16 v[100:103], v[182:185], v[202:205], v[100:103]
	v_mfma_f32_16x16x32_bf16 v[88:91], v[174:177], v[210:213], v[88:91]
	v_mfma_f32_16x16x32_bf16 v[84:87], v[182:185], v[210:213], v[84:87]
	v_mfma_f32_16x16x32_bf16 v[72:75], v[174:177], v[218:221], v[72:75]
	v_mfma_f32_16x16x32_bf16 v[68:71], v[182:185], v[218:221], v[68:71]
	s_setprio 2
	s_barrier
	s_add_i32 s36, s36, s41
	v_lshl_add_u64 v[6:7], v[154:155], 0, s[94:95]
	s_mov_b32 m0, s36
	ds_read_b128 v[190:193], v189 offset:49152
	ds_read_b128 v[194:197], v189 offset:50176
	ds_read_b128 v[198:201], v189 offset:51200
	ds_read_b128 v[202:205], v189 offset:52224
	ds_read_b128 v[206:209], v189 offset:53248
	ds_read_b128 v[210:213], v189 offset:54272
	ds_read_b128 v[214:217], v189 offset:55296
	ds_read_b128 v[218:221], v189 offset:56320
	global_load_lds_dwordx4 v[6:7], off
	s_add_i32 m0, s36, 0x2000
	s_add_u32 s42, s42, 0x80080
	v_lshl_add_u64 v[6:7], v[222:223], 0, s[94:95]
	s_addc_u32 s43, s43, 0
	s_add_i32 s36, s62, s41
	global_load_lds_dwordx4 v[6:7], off
	s_mov_b32 m0, s36
	v_lshl_add_u64 v[6:7], s[42:43], 0, v[160:161]
	global_load_lds_dwordx4 v[6:7], off
	s_add_i32 m0, s36, 0x2000
	v_lshl_add_u64 v[6:7], s[42:43], 0, v[156:157]
	global_load_lds_dwordx4 v[6:7], off
	s_mov_b32 m0, s48
	v_lshl_add_u64 v[6:7], v[224:225], 0, s[94:95]
	global_load_lds_dwordx4 v[6:7], off
	s_mov_b32 m0, s52
	v_lshl_add_u64 v[6:7], v[226:227], 0, s[94:95]
	global_load_lds_dwordx4 v[6:7], off
	s_waitcnt vmcnt(8)
	s_waitcnt lgkmcnt(0)
	s_barrier
	s_setprio 1
	s_waitcnt lgkmcnt(0)
	v_mfma_f32_16x16x32_bf16 v[64:67], v[138:141], v[190:193], v[64:67]
	v_mfma_f32_16x16x32_bf16 v[60:63], v[146:149], v[190:193], v[60:63]
	v_mfma_f32_16x16x32_bf16 v[48:51], v[138:141], v[198:201], v[48:51]
	v_mfma_f32_16x16x32_bf16 v[44:47], v[146:149], v[198:201], v[44:47]
	v_mfma_f32_16x16x32_bf16 v[32:35], v[138:141], v[206:209], v[32:35]
	v_mfma_f32_16x16x32_bf16 v[28:31], v[146:149], v[206:209], v[28:31]
	v_mfma_f32_16x16x32_bf16 v[16:19], v[138:141], v[214:217], v[16:19]
	v_mfma_f32_16x16x32_bf16 v[12:15], v[146:149], v[214:217], v[12:15]
	v_mfma_f32_16x16x32_bf16 v[64:67], v[142:145], v[194:197], v[64:67]
	v_mfma_f32_16x16x32_bf16 v[60:63], v[150:153], v[194:197], v[60:63]
	v_mfma_f32_16x16x32_bf16 v[48:51], v[142:145], v[202:205], v[48:51]
	v_mfma_f32_16x16x32_bf16 v[44:47], v[150:153], v[202:205], v[44:47]
	v_mfma_f32_16x16x32_bf16 v[32:35], v[142:145], v[210:213], v[32:35]
	v_mfma_f32_16x16x32_bf16 v[28:31], v[150:153], v[210:213], v[28:31]
	v_mfma_f32_16x16x32_bf16 v[16:19], v[142:145], v[218:221], v[16:19]
	v_mfma_f32_16x16x32_bf16 v[12:15], v[150:153], v[218:221], v[12:15]
	s_setprio 0
	s_setprio 1
	v_mfma_f32_16x16x32_bf16 v[56:59], v[170:173], v[190:193], v[56:59]
	v_mfma_f32_16x16x32_bf16 v[52:55], v[178:181], v[190:193], v[52:55]
	v_mfma_f32_16x16x32_bf16 v[40:43], v[170:173], v[198:201], v[40:43]
	v_mfma_f32_16x16x32_bf16 v[36:39], v[178:181], v[198:201], v[36:39]
	v_mfma_f32_16x16x32_bf16 v[24:27], v[170:173], v[206:209], v[24:27]
	v_mfma_f32_16x16x32_bf16 v[20:23], v[178:181], v[206:209], v[20:23]
	v_mfma_f32_16x16x32_bf16 v[6:9], v[170:173], v[214:217], v[8:11]
	v_mfma_f32_16x16x32_bf16 v[2:5], v[178:181], v[214:217], v[2:5]
	v_mfma_f32_16x16x32_bf16 v[56:59], v[174:177], v[194:197], v[56:59]
	v_mfma_f32_16x16x32_bf16 v[52:55], v[182:185], v[194:197], v[52:55]
	v_mfma_f32_16x16x32_bf16 v[40:43], v[174:177], v[202:205], v[40:43]
	v_mfma_f32_16x16x32_bf16 v[36:39], v[182:185], v[202:205], v[36:39]
	v_mfma_f32_16x16x32_bf16 v[24:27], v[174:177], v[210:213], v[24:27]
	v_mfma_f32_16x16x32_bf16 v[20:23], v[182:185], v[210:213], v[20:23]
	v_mfma_f32_16x16x32_bf16 v[8:11], v[174:177], v[218:221], v[6:9]
	v_mfma_f32_16x16x32_bf16 v[4:7], v[182:185], v[218:221], v[2:5]
	s_setprio 2
	s_barrier
	s_add_i32 s64, s64, 2
	s_add_u32 s38, s38, 0x100
	s_addc_u32 s39, s39, 0
	s_cmp_gt_u32 s64, 29
	s_cbranch_scc1 .LBB0_688

.LBB0_773:
	s_add_u32 s6, s12, 0xfff80080
	s_addc_u32 s7, s13, -1
	s_add_i32 s19, 0, 0x10000
	s_cmp_eq_u32 s18, 28
	s_cselect_b32 s15, s61, s7
	s_cselect_b32 s14, vcc_lo, s6
	s_cselect_b32 s7, s35, s17
	s_cselect_b32 s6, vcc_hi, s16
	s_add_i32 s80, 0, 0x14000
	v_add_u32_e32 v142, s19, v208
	v_add_u32_e32 v158, s80, v208
	ds_read_b128 v[130:133], v142
	ds_read_b128 v[134:137], v142 offset:1024
	ds_read_b128 v[138:141], v142 offset:2048
	ds_read_b128 v[142:145], v142 offset:3072
	ds_read_b128 v[146:149], v158
	ds_read_b128 v[150:153], v158 offset:1024
	ds_read_b128 v[154:157], v158 offset:2048
	ds_read_b128 v[158:161], v158 offset:3072
	v_lshl_add_u64 v[170:171], s[12:13], 0, v[184:185]
	s_add_i32 m0, s33, 0xc000
	ds_read_b128 v[162:165], v209
	ds_read_b128 v[166:169], v209 offset:1024
	ds_read_b128 v[176:179], v209 offset:2048
	ds_read_b128 v[186:189], v209 offset:3072
	ds_read_b128 v[190:193], v209 offset:4096
	ds_read_b128 v[194:197], v209 offset:5120
	ds_read_b128 v[198:201], v209 offset:6144
	ds_read_b128 v[202:205], v209 offset:7168
	global_load_lds_dwordx4 v[170:171], off
	s_add_i32 m0, s33, 0xe000
	v_lshl_add_u64 v[170:171], s[12:13], 0, v[182:183]
	global_load_lds_dwordx4 v[170:171], off
	s_waitcnt vmcnt(8)
	s_waitcnt lgkmcnt(0)
	s_barrier
	s_setprio 1
	s_waitcnt lgkmcnt(0)
	v_mfma_f32_16x16x32_bf16 v[122:125], v[130:133], v[162:165], v[122:125]
	v_mfma_f32_16x16x32_bf16 v[90:93], v[138:141], v[162:165], v[90:93]
	v_mfma_f32_16x16x32_bf16 v[110:113], v[130:133], v[176:179], v[110:113]
	v_mfma_f32_16x16x32_bf16 v[46:49], v[138:141], v[176:179], v[46:49]
	v_mfma_f32_16x16x32_bf16 v[106:109], v[130:133], v[190:193], v[106:109]
	v_mfma_f32_16x16x32_bf16 v[42:45], v[138:141], v[190:193], v[42:45]
	v_mfma_f32_16x16x32_bf16 v[126:129], v[130:133], v[198:201], v[126:129]
	v_mfma_f32_16x16x32_bf16 v[54:57], v[138:141], v[198:201], v[54:57]
	v_mfma_f32_16x16x32_bf16 v[122:125], v[134:137], v[166:169], v[122:125]
	v_mfma_f32_16x16x32_bf16 v[90:93], v[142:145], v[166:169], v[90:93]
	v_mfma_f32_16x16x32_bf16 v[110:113], v[134:137], v[186:189], v[110:113]
	v_mfma_f32_16x16x32_bf16 v[46:49], v[142:145], v[186:189], v[46:49]
	v_mfma_f32_16x16x32_bf16 v[106:109], v[134:137], v[194:197], v[106:109]
	v_mfma_f32_16x16x32_bf16 v[42:45], v[142:145], v[194:197], v[42:45]
	v_mfma_f32_16x16x32_bf16 v[126:129], v[134:137], v[202:205], v[126:129]
	v_mfma_f32_16x16x32_bf16 v[54:57], v[142:145], v[202:205], v[54:57]
	s_setprio 0
	s_setprio 1
	v_mfma_f32_16x16x32_bf16 v[114:117], v[146:149], v[162:165], v[114:117]
	v_mfma_f32_16x16x32_bf16 v[94:97], v[154:157], v[162:165], v[94:97]
	v_mfma_f32_16x16x32_bf16 v[102:105], v[146:149], v[176:179], v[102:105]
	v_mfma_f32_16x16x32_bf16 v[38:41], v[154:157], v[176:179], v[38:41]
	v_mfma_f32_16x16x32_bf16 v[98:101], v[146:149], v[190:193], v[98:101]
	v_mfma_f32_16x16x32_bf16 v[34:37], v[154:157], v[190:193], v[34:37]
	v_mfma_f32_16x16x32_bf16 v[118:121], v[146:149], v[198:201], v[118:121]
	v_mfma_f32_16x16x32_bf16 v[50:53], v[154:157], v[198:201], v[50:53]
	v_mfma_f32_16x16x32_bf16 v[114:117], v[150:153], v[166:169], v[114:117]
	v_mfma_f32_16x16x32_bf16 v[94:97], v[158:161], v[166:169], v[94:97]
	v_mfma_f32_16x16x32_bf16 v[102:105], v[150:153], v[186:189], v[102:105]
	v_mfma_f32_16x16x32_bf16 v[38:41], v[158:161], v[186:189], v[38:41]
	v_mfma_f32_16x16x32_bf16 v[98:101], v[150:153], v[194:197], v[98:101]
	v_mfma_f32_16x16x32_bf16 v[34:37], v[158:161], v[194:197], v[34:37]
	v_mfma_f32_16x16x32_bf16 v[118:121], v[150:153], v[202:205], v[118:121]
	v_mfma_f32_16x16x32_bf16 v[50:53], v[158:161], v[202:205], v[50:53]
	s_setprio 2
	s_barrier
	s_add_i32 s19, s19, s41
	v_lshl_add_u64 v[170:171], s[6:7], 0, v[0:1]
	s_mov_b32 m0, s19
	ds_read_b128 v[162:165], v209 offset:16384
	ds_read_b128 v[166:169], v209 offset:17408
	ds_read_b128 v[176:179], v209 offset:18432
	ds_read_b128 v[186:189], v209 offset:19456
	ds_read_b128 v[190:193], v209 offset:20480
	ds_read_b128 v[194:197], v209 offset:21504
	ds_read_b128 v[198:201], v209 offset:22528
	ds_read_b128 v[202:205], v209 offset:23552
	global_load_lds_dwordx4 v[170:171], off
	s_add_i32 m0, s19, 0x2000
	s_add_u32 s24, s6, 0x80000
	v_lshl_add_u64 v[210:211], s[6:7], 0, v[172:173]
	s_addc_u32 s25, s7, 0
	s_add_i32 s19, s80, s41
	global_load_lds_dwordx4 v[210:211], off
	v_lshl_add_u64 v[212:213], s[24:25], 0, v[0:1]
	s_mov_b32 m0, s19
	v_lshl_add_u64 v[214:215], s[14:15], 0, v[174:175]
	global_load_lds_dwordx4 v[212:213], off
	s_add_i32 m0, s19, 0x2000
	v_lshl_add_u64 v[212:213], s[24:25], 0, v[172:173]
	global_load_lds_dwordx4 v[212:213], off
	s_mov_b32 m0, s33
	v_lshl_add_u64 v[212:213], s[14:15], 0, v[180:181]
	global_load_lds_dwordx4 v[212:213], off
	s_mov_b32 m0, s59
	s_nop 0
	global_load_lds_dwordx4 v[214:215], off
	s_waitcnt vmcnt(8)
	s_waitcnt lgkmcnt(0)
	s_barrier
	s_setprio 1
	s_waitcnt lgkmcnt(0)
	v_mfma_f32_16x16x32_bf16 v[78:81], v[130:133], v[162:165], v[78:81]
	v_mfma_f32_16x16x32_bf16 v[22:25], v[138:141], v[162:165], v[22:25]
	v_mfma_f32_16x16x32_bf16 v[70:73], v[130:133], v[176:179], v[70:73]
	v_mfma_f32_16x16x32_bf16 v[18:21], v[138:141], v[176:179], v[18:21]
	v_mfma_f32_16x16x32_bf16 v[66:69], v[130:133], v[190:193], v[66:69]
	v_mfma_f32_16x16x32_bf16 v[14:17], v[138:141], v[190:193], v[14:17]
	v_mfma_f32_16x16x32_bf16 v[86:89], v[130:133], v[198:201], v[86:89]
	v_mfma_f32_16x16x32_bf16 v[30:33], v[138:141], v[198:201], v[30:33]
	v_mfma_f32_16x16x32_bf16 v[78:81], v[134:137], v[166:169], v[78:81]
	v_mfma_f32_16x16x32_bf16 v[22:25], v[142:145], v[166:169], v[22:25]
	v_mfma_f32_16x16x32_bf16 v[70:73], v[134:137], v[186:189], v[70:73]
	v_mfma_f32_16x16x32_bf16 v[18:21], v[142:145], v[186:189], v[18:21]
	v_mfma_f32_16x16x32_bf16 v[66:69], v[134:137], v[194:197], v[66:69]
	v_mfma_f32_16x16x32_bf16 v[14:17], v[142:145], v[194:197], v[14:17]
	v_mfma_f32_16x16x32_bf16 v[86:89], v[134:137], v[202:205], v[86:89]
	v_mfma_f32_16x16x32_bf16 v[30:33], v[142:145], v[202:205], v[30:33]
	s_setprio 0
	s_setprio 1
	v_mfma_f32_16x16x32_bf16 v[74:77], v[146:149], v[162:165], v[74:77]
	v_mfma_f32_16x16x32_bf16 v[10:13], v[154:157], v[162:165], v[10:13]
	v_mfma_f32_16x16x32_bf16 v[62:65], v[146:149], v[176:179], v[62:65]
	v_mfma_f32_16x16x32_bf16 v[6:9], v[154:157], v[176:179], v[6:9]
	v_mfma_f32_16x16x32_bf16 v[58:61], v[146:149], v[190:193], v[58:61]
	v_mfma_f32_16x16x32_bf16 v[2:5], v[154:157], v[190:193], v[2:5]
	v_mfma_f32_16x16x32_bf16 v[82:85], v[146:149], v[198:201], v[82:85]
	v_mfma_f32_16x16x32_bf16 v[26:29], v[154:157], v[198:201], v[26:29]
	v_mfma_f32_16x16x32_bf16 v[74:77], v[150:153], v[166:169], v[74:77]
	v_mfma_f32_16x16x32_bf16 v[10:13], v[158:161], v[166:169], v[10:13]
	v_mfma_f32_16x16x32_bf16 v[62:65], v[150:153], v[186:189], v[62:65]
	v_mfma_f32_16x16x32_bf16 v[6:9], v[158:161], v[186:189], v[6:9]
	v_mfma_f32_16x16x32_bf16 v[58:61], v[150:153], v[194:197], v[58:61]
	v_mfma_f32_16x16x32_bf16 v[2:5], v[158:161], v[194:197], v[2:5]
	v_mfma_f32_16x16x32_bf16 v[82:85], v[150:153], v[202:205], v[82:85]
	v_mfma_f32_16x16x32_bf16 v[26:29], v[158:161], v[202:205], v[26:29]
	s_setprio 2
	s_barrier
	s_add_i32 s19, 0, 0x18000
	s_add_i32 s24, 0, 0x1c000
	v_add_u32_e32 v142, s19, v208
	v_add_u32_e32 v158, s24, v208
	ds_read_b128 v[130:133], v142
	ds_read_b128 v[134:137], v142 offset:1024
	ds_read_b128 v[138:141], v142 offset:2048
	ds_read_b128 v[142:145], v142 offset:3072
	ds_read_b128 v[146:149], v158
	ds_read_b128 v[150:153], v158 offset:1024
	ds_read_b128 v[154:157], v158 offset:2048
	ds_read_b128 v[158:161], v158 offset:3072
	s_add_u32 s14, s14, 0x80000
	s_addc_u32 s15, s15, 0
	s_mov_b32 m0, s76
	v_lshl_add_u64 v[216:217], s[14:15], 0, v[180:181]
	ds_read_b128 v[162:165], v209 offset:32768
	ds_read_b128 v[166:169], v209 offset:33792
	ds_read_b128 v[176:179], v209 offset:34816
	ds_read_b128 v[186:189], v209 offset:35840
	ds_read_b128 v[190:193], v209 offset:36864
	ds_read_b128 v[194:197], v209 offset:37888
	ds_read_b128 v[198:201], v209 offset:38912
	ds_read_b128 v[202:205], v209 offset:39936
	global_load_lds_dwordx4 v[216:217], off
	s_mov_b32 m0, s77
	v_lshl_add_u64 v[216:217], s[14:15], 0, v[174:175]
	global_load_lds_dwordx4 v[216:217], off
	s_waitcnt vmcnt(8)
	s_waitcnt lgkmcnt(0)
	s_barrier
	s_setprio 1
	s_waitcnt lgkmcnt(0)
	v_mfma_f32_16x16x32_bf16 v[122:125], v[130:133], v[162:165], v[122:125]
	v_mfma_f32_16x16x32_bf16 v[90:93], v[138:141], v[162:165], v[90:93]
	v_mfma_f32_16x16x32_bf16 v[110:113], v[130:133], v[176:179], v[110:113]
	v_mfma_f32_16x16x32_bf16 v[46:49], v[138:141], v[176:179], v[46:49]
	v_mfma_f32_16x16x32_bf16 v[106:109], v[130:133], v[190:193], v[106:109]
	v_mfma_f32_16x16x32_bf16 v[42:45], v[138:141], v[190:193], v[42:45]
	v_mfma_f32_16x16x32_bf16 v[126:129], v[130:133], v[198:201], v[126:129]
	v_mfma_f32_16x16x32_bf16 v[54:57], v[138:141], v[198:201], v[54:57]
	v_mfma_f32_16x16x32_bf16 v[122:125], v[134:137], v[166:169], v[122:125]
	v_mfma_f32_16x16x32_bf16 v[90:93], v[142:145], v[166:169], v[90:93]
	v_mfma_f32_16x16x32_bf16 v[110:113], v[134:137], v[186:189], v[110:113]
	v_mfma_f32_16x16x32_bf16 v[46:49], v[142:145], v[186:189], v[46:49]
	v_mfma_f32_16x16x32_bf16 v[106:109], v[134:137], v[194:197], v[106:109]
	v_mfma_f32_16x16x32_bf16 v[42:45], v[142:145], v[194:197], v[42:45]
	v_mfma_f32_16x16x32_bf16 v[126:129], v[134:137], v[202:205], v[126:129]
	v_mfma_f32_16x16x32_bf16 v[54:57], v[142:145], v[202:205], v[54:57]
	s_setprio 0
	s_setprio 1
	v_mfma_f32_16x16x32_bf16 v[114:117], v[146:149], v[162:165], v[114:117]
	v_mfma_f32_16x16x32_bf16 v[94:97], v[154:157], v[162:165], v[94:97]
	v_mfma_f32_16x16x32_bf16 v[102:105], v[146:149], v[176:179], v[102:105]
	v_mfma_f32_16x16x32_bf16 v[38:41], v[154:157], v[176:179], v[38:41]
	v_mfma_f32_16x16x32_bf16 v[98:101], v[146:149], v[190:193], v[98:101]
	v_mfma_f32_16x16x32_bf16 v[34:37], v[154:157], v[190:193], v[34:37]
	v_mfma_f32_16x16x32_bf16 v[118:121], v[146:149], v[198:201], v[118:121]
	v_mfma_f32_16x16x32_bf16 v[50:53], v[154:157], v[198:201], v[50:53]
	v_mfma_f32_16x16x32_bf16 v[114:117], v[150:153], v[166:169], v[114:117]
	v_mfma_f32_16x16x32_bf16 v[94:97], v[158:161], v[166:169], v[94:97]
	v_mfma_f32_16x16x32_bf16 v[102:105], v[150:153], v[186:189], v[102:105]
	v_mfma_f32_16x16x32_bf16 v[38:41], v[158:161], v[186:189], v[38:41]
	v_mfma_f32_16x16x32_bf16 v[98:101], v[150:153], v[194:197], v[98:101]
	v_mfma_f32_16x16x32_bf16 v[34:37], v[158:161], v[194:197], v[34:37]
	v_mfma_f32_16x16x32_bf16 v[118:121], v[150:153], v[202:205], v[118:121]
	v_mfma_f32_16x16x32_bf16 v[50:53], v[158:161], v[202:205], v[50:53]
	s_setprio 2
	s_barrier
	s_add_i32 s14, s19, s41
	v_lshl_add_u64 v[170:171], v[170:171], 0, s[94:95]
	s_mov_b32 m0, s14
	ds_read_b128 v[162:165], v209 offset:49152
	ds_read_b128 v[166:169], v209 offset:50176
	ds_read_b128 v[176:179], v209 offset:51200
	ds_read_b128 v[186:189], v209 offset:52224
	ds_read_b128 v[190:193], v209 offset:53248
	ds_read_b128 v[194:197], v209 offset:54272
	ds_read_b128 v[198:201], v209 offset:55296
	ds_read_b128 v[202:205], v209 offset:56320
	global_load_lds_dwordx4 v[170:171], off
	s_add_i32 m0, s14, 0x2000
	s_add_u32 s6, s6, 0x80080
	v_lshl_add_u64 v[170:171], v[210:211], 0, s[94:95]
	s_addc_u32 s7, s7, 0
	s_add_i32 s14, s24, s41
	global_load_lds_dwordx4 v[170:171], off
	s_mov_b32 m0, s14
	v_lshl_add_u64 v[170:171], s[6:7], 0, v[0:1]
	global_load_lds_dwordx4 v[170:171], off
	s_add_i32 m0, s14, 0x2000
	v_lshl_add_u64 v[170:171], s[6:7], 0, v[172:173]
	global_load_lds_dwordx4 v[170:171], off
	s_mov_b32 m0, s28
	v_lshl_add_u64 v[170:171], v[212:213], 0, s[94:95]
	global_load_lds_dwordx4 v[170:171], off
	s_mov_b32 m0, s82
	v_lshl_add_u64 v[170:171], v[214:215], 0, s[94:95]
	global_load_lds_dwordx4 v[170:171], off
	s_waitcnt vmcnt(8)
	s_waitcnt lgkmcnt(0)
	s_barrier
	s_setprio 1
	s_waitcnt lgkmcnt(0)
	v_mfma_f32_16x16x32_bf16 v[78:81], v[130:133], v[162:165], v[78:81]
	v_mfma_f32_16x16x32_bf16 v[22:25], v[138:141], v[162:165], v[22:25]
	v_mfma_f32_16x16x32_bf16 v[70:73], v[130:133], v[176:179], v[70:73]
	v_mfma_f32_16x16x32_bf16 v[18:21], v[138:141], v[176:179], v[18:21]
	v_mfma_f32_16x16x32_bf16 v[66:69], v[130:133], v[190:193], v[66:69]
	v_mfma_f32_16x16x32_bf16 v[14:17], v[138:141], v[190:193], v[14:17]
	v_mfma_f32_16x16x32_bf16 v[86:89], v[130:133], v[198:201], v[86:89]
	v_mfma_f32_16x16x32_bf16 v[30:33], v[138:141], v[198:201], v[30:33]
	v_mfma_f32_16x16x32_bf16 v[78:81], v[134:137], v[166:169], v[78:81]
	v_mfma_f32_16x16x32_bf16 v[22:25], v[142:145], v[166:169], v[22:25]
	v_mfma_f32_16x16x32_bf16 v[70:73], v[134:137], v[186:189], v[70:73]
	v_mfma_f32_16x16x32_bf16 v[18:21], v[142:145], v[186:189], v[18:21]
	v_mfma_f32_16x16x32_bf16 v[66:69], v[134:137], v[194:197], v[66:69]
	v_mfma_f32_16x16x32_bf16 v[14:17], v[142:145], v[194:197], v[14:17]
	v_mfma_f32_16x16x32_bf16 v[86:89], v[134:137], v[202:205], v[86:89]
	v_mfma_f32_16x16x32_bf16 v[30:33], v[142:145], v[202:205], v[30:33]
	s_setprio 0
	s_setprio 1
	v_mfma_f32_16x16x32_bf16 v[74:77], v[146:149], v[162:165], v[74:77]
	v_mfma_f32_16x16x32_bf16 v[10:13], v[154:157], v[162:165], v[10:13]
	v_mfma_f32_16x16x32_bf16 v[62:65], v[146:149], v[176:179], v[62:65]
	v_mfma_f32_16x16x32_bf16 v[6:9], v[154:157], v[176:179], v[6:9]
	v_mfma_f32_16x16x32_bf16 v[58:61], v[146:149], v[190:193], v[58:61]
	v_mfma_f32_16x16x32_bf16 v[2:5], v[154:157], v[190:193], v[2:5]
	v_mfma_f32_16x16x32_bf16 v[82:85], v[146:149], v[198:201], v[82:85]
	v_mfma_f32_16x16x32_bf16 v[26:29], v[154:157], v[198:201], v[26:29]
	v_mfma_f32_16x16x32_bf16 v[74:77], v[150:153], v[166:169], v[74:77]
	v_mfma_f32_16x16x32_bf16 v[10:13], v[158:161], v[166:169], v[10:13]
	v_mfma_f32_16x16x32_bf16 v[62:65], v[150:153], v[186:189], v[62:65]
	v_mfma_f32_16x16x32_bf16 v[6:9], v[158:161], v[186:189], v[6:9]
	v_mfma_f32_16x16x32_bf16 v[58:61], v[150:153], v[194:197], v[58:61]
	v_mfma_f32_16x16x32_bf16 v[2:5], v[158:161], v[194:197], v[2:5]
	v_mfma_f32_16x16x32_bf16 v[82:85], v[150:153], v[202:205], v[82:85]
	v_mfma_f32_16x16x32_bf16 v[26:29], v[158:161], v[202:205], v[26:29]
	s_setprio 2
	s_barrier
	s_add_i32 s18, s18, 2
	s_add_u32 s16, s16, 0x100
	s_addc_u32 s17, s17, 0
	s_add_u32 s12, s12, 0x100
	s_addc_u32 s13, s13, 0
	s_cmp_gt_u32 s18, 29
	s_cbranch_scc0 .LBB0_773
	s_and_b64 vcc, exec, s[72:73]
	s_cbranch_vccz .LBB0_776
	s_barrier

.LBB0_924:
	s_add_u32 s10, s12, 0x100
	s_addc_u32 s11, s13, 0
	s_add_i32 s67, 0, 0x10000
	s_cmpk_eq_i32 s66, 0x54
	s_cselect_b32 s45, s39, s11
	s_cselect_b32 s44, s38, s10
	s_cselect_b32 s15, s43, s65
	s_cselect_b32 s14, s42, s64
	s_add_i32 s68, 0, 0x14000
	v_add_u32_e32 v142, s67, v190
	v_add_u32_e32 v168, s68, v190
	ds_read_b128 v[122:125], v142
	ds_read_b128 v[126:129], v142 offset:1024
	ds_read_b128 v[138:141], v142 offset:2048
	ds_read_b128 v[142:145], v142 offset:3072
	ds_read_b128 v[146:149], v168
	ds_read_b128 v[150:153], v168 offset:1024
	ds_read_b128 v[154:157], v168 offset:2048
	ds_read_b128 v[168:171], v168 offset:3072
	v_lshl_add_u64 v[208:209], s[12:13], 0, v[166:167]
	s_add_i32 m0, s40, 0xc000
	ds_read_b128 v[172:175], v191
	ds_read_b128 v[176:179], v191 offset:1024
	ds_read_b128 v[180:183], v191 offset:2048
	ds_read_b128 v[184:187], v191 offset:3072
	ds_read_b128 v[192:195], v191 offset:4096
	ds_read_b128 v[196:199], v191 offset:5120
	ds_read_b128 v[200:203], v191 offset:6144
	ds_read_b128 v[204:207], v191 offset:7168
	global_load_lds_dwordx4 v[208:209], off
	s_add_i32 m0, s40, 0xe000
	v_lshl_add_u64 v[208:209], s[12:13], 0, v[164:165]
	global_load_lds_dwordx4 v[208:209], off
	s_waitcnt vmcnt(8)
	s_waitcnt lgkmcnt(0)
	s_barrier
	s_setprio 1
	s_waitcnt lgkmcnt(0)
	v_mfma_f32_16x16x32_bf16 v[134:137], v[122:125], v[172:175], v[134:137]
	v_mfma_f32_16x16x32_bf16 v[130:133], v[138:141], v[172:175], v[130:133]
	v_mfma_f32_16x16x32_bf16 v[110:113], v[122:125], v[180:183], v[110:113]
	v_mfma_f32_16x16x32_bf16 v[106:109], v[138:141], v[180:183], v[106:109]
	v_mfma_f32_16x16x32_bf16 v[94:97], v[122:125], v[192:195], v[94:97]
	v_mfma_f32_16x16x32_bf16 v[90:93], v[138:141], v[192:195], v[90:93]
	v_mfma_f32_16x16x32_bf16 v[78:81], v[122:125], v[200:203], v[78:81]
	v_mfma_f32_16x16x32_bf16 v[74:77], v[138:141], v[200:203], v[74:77]
	v_mfma_f32_16x16x32_bf16 v[134:137], v[126:129], v[176:179], v[134:137]
	v_mfma_f32_16x16x32_bf16 v[130:133], v[142:145], v[176:179], v[130:133]
	v_mfma_f32_16x16x32_bf16 v[110:113], v[126:129], v[184:187], v[110:113]
	v_mfma_f32_16x16x32_bf16 v[106:109], v[142:145], v[184:187], v[106:109]
	v_mfma_f32_16x16x32_bf16 v[94:97], v[126:129], v[196:199], v[94:97]
	v_mfma_f32_16x16x32_bf16 v[90:93], v[142:145], v[196:199], v[90:93]
	v_mfma_f32_16x16x32_bf16 v[78:81], v[126:129], v[204:207], v[78:81]
	v_mfma_f32_16x16x32_bf16 v[74:77], v[142:145], v[204:207], v[74:77]
	s_setprio 0
	s_setprio 1
	v_mfma_f32_16x16x32_bf16 v[118:121], v[146:149], v[172:175], v[118:121]
	v_mfma_f32_16x16x32_bf16 v[114:117], v[154:157], v[172:175], v[114:117]
	v_mfma_f32_16x16x32_bf16 v[102:105], v[146:149], v[180:183], v[102:105]
	v_mfma_f32_16x16x32_bf16 v[98:101], v[154:157], v[180:183], v[98:101]
	v_mfma_f32_16x16x32_bf16 v[86:89], v[146:149], v[192:195], v[86:89]
	v_mfma_f32_16x16x32_bf16 v[82:85], v[154:157], v[192:195], v[82:85]
	v_mfma_f32_16x16x32_bf16 v[70:73], v[146:149], v[200:203], v[70:73]
	v_mfma_f32_16x16x32_bf16 v[66:69], v[154:157], v[200:203], v[66:69]
	v_mfma_f32_16x16x32_bf16 v[118:121], v[150:153], v[176:179], v[118:121]
	v_mfma_f32_16x16x32_bf16 v[114:117], v[168:171], v[176:179], v[114:117]
	v_mfma_f32_16x16x32_bf16 v[102:105], v[150:153], v[184:187], v[102:105]
	v_mfma_f32_16x16x32_bf16 v[98:101], v[168:171], v[184:187], v[98:101]
	v_mfma_f32_16x16x32_bf16 v[86:89], v[150:153], v[196:199], v[86:89]
	v_mfma_f32_16x16x32_bf16 v[82:85], v[168:171], v[196:199], v[82:85]
	v_mfma_f32_16x16x32_bf16 v[70:73], v[150:153], v[204:207], v[70:73]
	v_mfma_f32_16x16x32_bf16 v[66:69], v[168:171], v[204:207], v[66:69]
	s_setprio 2
	s_barrier
	s_add_i32 s12, s67, s37
	v_lshl_add_u64 v[208:209], s[14:15], 0, v[0:1]
	s_mov_b32 m0, s12
	ds_read_b128 v[172:175], v191 offset:16384
	ds_read_b128 v[176:179], v191 offset:17408
	ds_read_b128 v[180:183], v191 offset:18432
	ds_read_b128 v[184:187], v191 offset:19456
	ds_read_b128 v[192:195], v191 offset:20480
	ds_read_b128 v[196:199], v191 offset:21504
	ds_read_b128 v[200:203], v191 offset:22528
	ds_read_b128 v[204:207], v191 offset:23552
	global_load_lds_dwordx4 v[208:209], off
	s_add_i32 m0, s12, 0x2000
	s_add_u32 s12, s14, 0x160000
	v_lshl_add_u64 v[210:211], s[14:15], 0, v[158:159]
	s_addc_u32 s13, s15, 0
	s_add_i32 s67, s68, s37
	global_load_lds_dwordx4 v[210:211], off
	v_lshl_add_u64 v[212:213], s[12:13], 0, v[0:1]
	s_mov_b32 m0, s67
	v_lshl_add_u64 v[214:215], s[44:45], 0, v[160:161]
	global_load_lds_dwordx4 v[212:213], off
	s_add_i32 m0, s67, 0x2000
	v_lshl_add_u64 v[212:213], s[12:13], 0, v[158:159]
	global_load_lds_dwordx4 v[212:213], off
	s_mov_b32 m0, s40
	v_lshl_add_u64 v[212:213], s[44:45], 0, v[162:163]
	global_load_lds_dwordx4 v[212:213], off
	s_mov_b32 m0, s41
	s_nop 0
	global_load_lds_dwordx4 v[214:215], off
	s_waitcnt vmcnt(8)
	s_waitcnt lgkmcnt(0)
	s_barrier
	s_setprio 1
	s_waitcnt lgkmcnt(0)
	v_mfma_f32_16x16x32_bf16 v[62:65], v[122:125], v[172:175], v[62:65]
	v_mfma_f32_16x16x32_bf16 v[58:61], v[138:141], v[172:175], v[58:61]
	v_mfma_f32_16x16x32_bf16 v[46:49], v[122:125], v[180:183], v[46:49]
	v_mfma_f32_16x16x32_bf16 v[42:45], v[138:141], v[180:183], v[42:45]
	v_mfma_f32_16x16x32_bf16 v[30:33], v[122:125], v[192:195], v[30:33]
	v_mfma_f32_16x16x32_bf16 v[26:29], v[138:141], v[192:195], v[26:29]
	v_mfma_f32_16x16x32_bf16 v[14:17], v[122:125], v[200:203], v[14:17]
	v_mfma_f32_16x16x32_bf16 v[10:13], v[138:141], v[200:203], v[10:13]
	v_mfma_f32_16x16x32_bf16 v[62:65], v[126:129], v[176:179], v[62:65]
	v_mfma_f32_16x16x32_bf16 v[58:61], v[142:145], v[176:179], v[58:61]
	v_mfma_f32_16x16x32_bf16 v[46:49], v[126:129], v[184:187], v[46:49]
	v_mfma_f32_16x16x32_bf16 v[42:45], v[142:145], v[184:187], v[42:45]
	v_mfma_f32_16x16x32_bf16 v[30:33], v[126:129], v[196:199], v[30:33]
	v_mfma_f32_16x16x32_bf16 v[26:29], v[142:145], v[196:199], v[26:29]
	v_mfma_f32_16x16x32_bf16 v[14:17], v[126:129], v[204:207], v[14:17]
	v_mfma_f32_16x16x32_bf16 v[10:13], v[142:145], v[204:207], v[10:13]
	s_setprio 0
	s_setprio 1
	v_mfma_f32_16x16x32_bf16 v[54:57], v[146:149], v[172:175], v[54:57]
	v_mfma_f32_16x16x32_bf16 v[50:53], v[154:157], v[172:175], v[50:53]
	v_mfma_f32_16x16x32_bf16 v[38:41], v[146:149], v[180:183], v[38:41]
	v_mfma_f32_16x16x32_bf16 v[34:37], v[154:157], v[180:183], v[34:37]
	v_mfma_f32_16x16x32_bf16 v[22:25], v[146:149], v[192:195], v[22:25]
	v_mfma_f32_16x16x32_bf16 v[18:21], v[154:157], v[192:195], v[18:21]
	v_mfma_f32_16x16x32_bf16 v[6:9], v[146:149], v[200:203], v[6:9]
	v_mfma_f32_16x16x32_bf16 v[2:5], v[154:157], v[200:203], v[2:5]
	v_mfma_f32_16x16x32_bf16 v[54:57], v[150:153], v[176:179], v[54:57]
	v_mfma_f32_16x16x32_bf16 v[50:53], v[168:171], v[176:179], v[50:53]
	v_mfma_f32_16x16x32_bf16 v[38:41], v[150:153], v[184:187], v[38:41]
	v_mfma_f32_16x16x32_bf16 v[34:37], v[168:171], v[184:187], v[34:37]
	v_mfma_f32_16x16x32_bf16 v[22:25], v[150:153], v[196:199], v[22:25]
	v_mfma_f32_16x16x32_bf16 v[18:21], v[168:171], v[196:199], v[18:21]
	v_mfma_f32_16x16x32_bf16 v[6:9], v[150:153], v[204:207], v[6:9]
	v_mfma_f32_16x16x32_bf16 v[2:5], v[168:171], v[204:207], v[2:5]
	s_setprio 2
	s_barrier
	s_add_i32 s67, 0, 0x18000
	s_add_i32 s68, 0, 0x1c000
	v_add_u32_e32 v142, s67, v190
	v_add_u32_e32 v168, s68, v190
	ds_read_b128 v[122:125], v142
	ds_read_b128 v[126:129], v142 offset:1024
	ds_read_b128 v[138:141], v142 offset:2048
	ds_read_b128 v[142:145], v142 offset:3072
	ds_read_b128 v[146:149], v168
	ds_read_b128 v[150:153], v168 offset:1024
	ds_read_b128 v[154:157], v168 offset:2048
	ds_read_b128 v[168:171], v168 offset:3072
	s_add_u32 s12, s44, 0x160000
	s_addc_u32 s13, s45, 0
	s_mov_b32 m0, s48
	v_lshl_add_u64 v[216:217], s[12:13], 0, v[162:163]
	ds_read_b128 v[172:175], v191 offset:32768
	ds_read_b128 v[176:179], v191 offset:33792
	ds_read_b128 v[180:183], v191 offset:34816
	ds_read_b128 v[184:187], v191 offset:35840
	ds_read_b128 v[192:195], v191 offset:36864
	ds_read_b128 v[196:199], v191 offset:37888
	ds_read_b128 v[200:203], v191 offset:38912
	ds_read_b128 v[204:207], v191 offset:39936
	global_load_lds_dwordx4 v[216:217], off
	s_mov_b32 m0, s52
	v_lshl_add_u64 v[216:217], s[12:13], 0, v[160:161]
	global_load_lds_dwordx4 v[216:217], off
	s_waitcnt vmcnt(8)
	s_waitcnt lgkmcnt(0)
	s_barrier
	s_setprio 1
	s_waitcnt lgkmcnt(0)
	v_mfma_f32_16x16x32_bf16 v[134:137], v[122:125], v[172:175], v[134:137]
	v_mfma_f32_16x16x32_bf16 v[130:133], v[138:141], v[172:175], v[130:133]
	v_mfma_f32_16x16x32_bf16 v[110:113], v[122:125], v[180:183], v[110:113]
	v_mfma_f32_16x16x32_bf16 v[106:109], v[138:141], v[180:183], v[106:109]
	v_mfma_f32_16x16x32_bf16 v[94:97], v[122:125], v[192:195], v[94:97]
	v_mfma_f32_16x16x32_bf16 v[90:93], v[138:141], v[192:195], v[90:93]
	v_mfma_f32_16x16x32_bf16 v[78:81], v[122:125], v[200:203], v[78:81]
	v_mfma_f32_16x16x32_bf16 v[74:77], v[138:141], v[200:203], v[74:77]
	v_mfma_f32_16x16x32_bf16 v[134:137], v[126:129], v[176:179], v[134:137]
	v_mfma_f32_16x16x32_bf16 v[130:133], v[142:145], v[176:179], v[130:133]
	v_mfma_f32_16x16x32_bf16 v[110:113], v[126:129], v[184:187], v[110:113]
	v_mfma_f32_16x16x32_bf16 v[106:109], v[142:145], v[184:187], v[106:109]
	v_mfma_f32_16x16x32_bf16 v[94:97], v[126:129], v[196:199], v[94:97]
	v_mfma_f32_16x16x32_bf16 v[90:93], v[142:145], v[196:199], v[90:93]
	v_mfma_f32_16x16x32_bf16 v[78:81], v[126:129], v[204:207], v[78:81]
	v_mfma_f32_16x16x32_bf16 v[74:77], v[142:145], v[204:207], v[74:77]
	s_setprio 0
	s_setprio 1
	v_mfma_f32_16x16x32_bf16 v[118:121], v[146:149], v[172:175], v[118:121]
	v_mfma_f32_16x16x32_bf16 v[114:117], v[154:157], v[172:175], v[114:117]
	v_mfma_f32_16x16x32_bf16 v[102:105], v[146:149], v[180:183], v[102:105]
	v_mfma_f32_16x16x32_bf16 v[98:101], v[154:157], v[180:183], v[98:101]
	v_mfma_f32_16x16x32_bf16 v[86:89], v[146:149], v[192:195], v[86:89]
	v_mfma_f32_16x16x32_bf16 v[82:85], v[154:157], v[192:195], v[82:85]
	v_mfma_f32_16x16x32_bf16 v[70:73], v[146:149], v[200:203], v[70:73]
	v_mfma_f32_16x16x32_bf16 v[66:69], v[154:157], v[200:203], v[66:69]
	v_mfma_f32_16x16x32_bf16 v[118:121], v[150:153], v[176:179], v[118:121]
	v_mfma_f32_16x16x32_bf16 v[114:117], v[168:171], v[176:179], v[114:117]
	v_mfma_f32_16x16x32_bf16 v[102:105], v[150:153], v[184:187], v[102:105]
	v_mfma_f32_16x16x32_bf16 v[98:101], v[168:171], v[184:187], v[98:101]
	v_mfma_f32_16x16x32_bf16 v[86:89], v[150:153], v[196:199], v[86:89]
	v_mfma_f32_16x16x32_bf16 v[82:85], v[168:171], v[196:199], v[82:85]
	v_mfma_f32_16x16x32_bf16 v[70:73], v[150:153], v[204:207], v[70:73]
	v_mfma_f32_16x16x32_bf16 v[66:69], v[168:171], v[204:207], v[66:69]
	s_setprio 2
	s_barrier
	s_add_i32 s12, s67, s37
	v_lshl_add_u64 v[208:209], v[208:209], 0, s[94:95]
	s_mov_b32 m0, s12
	ds_read_b128 v[172:175], v191 offset:49152
	ds_read_b128 v[176:179], v191 offset:50176
	ds_read_b128 v[180:183], v191 offset:51200
	ds_read_b128 v[184:187], v191 offset:52224
	ds_read_b128 v[192:195], v191 offset:53248
	ds_read_b128 v[196:199], v191 offset:54272
	ds_read_b128 v[200:203], v191 offset:55296
	ds_read_b128 v[204:207], v191 offset:56320
	global_load_lds_dwordx4 v[208:209], off
	s_add_i32 m0, s12, 0x2000
	s_add_u32 s12, s14, 0x160080
	v_lshl_add_u64 v[208:209], v[210:211], 0, s[94:95]
	s_addc_u32 s13, s15, 0
	s_add_i32 s14, s68, s37
	global_load_lds_dwordx4 v[208:209], off
	s_mov_b32 m0, s14
	v_lshl_add_u64 v[208:209], s[12:13], 0, v[0:1]
	global_load_lds_dwordx4 v[208:209], off
	s_add_i32 m0, s14, 0x2000
	v_lshl_add_u64 v[208:209], s[12:13], 0, v[158:159]
	global_load_lds_dwordx4 v[208:209], off
	s_mov_b32 m0, s58
	v_lshl_add_u64 v[208:209], v[212:213], 0, s[94:95]
	global_load_lds_dwordx4 v[208:209], off
	s_mov_b32 m0, s59
	v_lshl_add_u64 v[208:209], v[214:215], 0, s[94:95]
	global_load_lds_dwordx4 v[208:209], off
	s_waitcnt vmcnt(8)
	s_waitcnt lgkmcnt(0)
	s_barrier
	s_setprio 1
	s_waitcnt lgkmcnt(0)
	v_mfma_f32_16x16x32_bf16 v[62:65], v[122:125], v[172:175], v[62:65]
	v_mfma_f32_16x16x32_bf16 v[58:61], v[138:141], v[172:175], v[58:61]
	v_mfma_f32_16x16x32_bf16 v[46:49], v[122:125], v[180:183], v[46:49]
	v_mfma_f32_16x16x32_bf16 v[42:45], v[138:141], v[180:183], v[42:45]
	v_mfma_f32_16x16x32_bf16 v[30:33], v[122:125], v[192:195], v[30:33]
	v_mfma_f32_16x16x32_bf16 v[26:29], v[138:141], v[192:195], v[26:29]
	v_mfma_f32_16x16x32_bf16 v[14:17], v[122:125], v[200:203], v[14:17]
	v_mfma_f32_16x16x32_bf16 v[10:13], v[138:141], v[200:203], v[10:13]
	v_mfma_f32_16x16x32_bf16 v[62:65], v[126:129], v[176:179], v[62:65]
	v_mfma_f32_16x16x32_bf16 v[58:61], v[142:145], v[176:179], v[58:61]
	v_mfma_f32_16x16x32_bf16 v[46:49], v[126:129], v[184:187], v[46:49]
	v_mfma_f32_16x16x32_bf16 v[42:45], v[142:145], v[184:187], v[42:45]
	v_mfma_f32_16x16x32_bf16 v[30:33], v[126:129], v[196:199], v[30:33]
	v_mfma_f32_16x16x32_bf16 v[26:29], v[142:145], v[196:199], v[26:29]
	v_mfma_f32_16x16x32_bf16 v[14:17], v[126:129], v[204:207], v[14:17]
	v_mfma_f32_16x16x32_bf16 v[10:13], v[142:145], v[204:207], v[10:13]
	s_setprio 0
	s_setprio 1
	v_mfma_f32_16x16x32_bf16 v[54:57], v[146:149], v[172:175], v[54:57]
	v_mfma_f32_16x16x32_bf16 v[50:53], v[154:157], v[172:175], v[50:53]
	v_mfma_f32_16x16x32_bf16 v[38:41], v[146:149], v[180:183], v[38:41]
	v_mfma_f32_16x16x32_bf16 v[34:37], v[154:157], v[180:183], v[34:37]
	v_mfma_f32_16x16x32_bf16 v[22:25], v[146:149], v[192:195], v[22:25]
	v_mfma_f32_16x16x32_bf16 v[18:21], v[154:157], v[192:195], v[18:21]
	v_mfma_f32_16x16x32_bf16 v[6:9], v[146:149], v[200:203], v[6:9]
	v_mfma_f32_16x16x32_bf16 v[2:5], v[154:157], v[200:203], v[2:5]
	v_mfma_f32_16x16x32_bf16 v[54:57], v[150:153], v[176:179], v[54:57]
	v_mfma_f32_16x16x32_bf16 v[50:53], v[168:171], v[176:179], v[50:53]
	v_mfma_f32_16x16x32_bf16 v[38:41], v[150:153], v[184:187], v[38:41]
	v_mfma_f32_16x16x32_bf16 v[34:37], v[168:171], v[184:187], v[34:37]
	v_mfma_f32_16x16x32_bf16 v[22:25], v[150:153], v[196:199], v[22:25]
	v_mfma_f32_16x16x32_bf16 v[18:21], v[168:171], v[196:199], v[18:21]
	v_mfma_f32_16x16x32_bf16 v[6:9], v[150:153], v[204:207], v[6:9]
	v_mfma_f32_16x16x32_bf16 v[2:5], v[168:171], v[204:207], v[2:5]
	s_setprio 2
	s_barrier
	s_add_i32 s66, s66, 2
	s_add_u32 s64, s64, 0x100
	s_addc_u32 s65, s65, 0
	s_cmpk_gt_u32 s66, 0x55
	s_mov_b64 s[12:13], s[10:11]
	s_cbranch_scc0 .LBB0_924
	s_and_b64 vcc, exec, s[24:25]
	s_cbranch_vccz .LBB0_927
	s_barrier
